# gates in lane-linear tile layout (P1 stores / P3 loads move 512 contiguous bytes per wave op) on top of P5/P6 full-line epilogues
# speedup vs baseline: 1.0312x; 1.0114x over previous
.LBB0_152:
	s_ashr_i32 s10, s38, 3
	s_ashr_i32 s11, s10, 31
	s_lshl_b64 s[72:73], s[10:11], 24
	v_lshl_add_u32 v192, s38, 8, v169
	s_cmp_gt_i32 s70, 15
	s_mov_b64 s[74:75], -1
	s_cbranch_scc0 .LBB0_159
	s_cmp_gt_u32 s70, 23
	s_cbranch_scc0 .LBB0_155
	s_ashr_i32 s100, s38, 3
	s_mul_i32 s100, s100, 0x2800000
	s_and_b32 s101, s38, 7
	s_lshl_b32 s101, s101, 4
	s_add_i32 s101, s101, s70
	s_sub_i32 s101, s101, 24
	s_lshl_b32 s101, s101, 16
	s_add_u32 s100, s100, s101
	s_add_u32 s100, s100, 0x9a00000
	s_add_u32 s100, s30, s100
	s_addc_u32 s101, s31, 0
	v_and_b32_e32 v253, 63, v168
	v_lshlrev_b32_e32 v253, 3, v253
	v_lshrrev_b32_e32 v252, 6, v168
	v_lshl_or_b32 v253, v252, 10, v253
	v_lshl_add_u32 v178, s70, 8, v183
	v_lshl_add_u64 v[18:19], v[178:179], 2, s[24:25]
	global_load_dwordx4 v[0:3], v[18:19], off offset:16
	global_load_dwordx4 v[4:7], v[18:19], off
	s_mov_b32 s38, 0xc0ffd1be
	v_mov_b64_e32 v[20:21], s[38:39]
	v_xor_b32_e32 v25, 0x80000000, v155
	v_xor_b32_e32 v24, 0x80000000, v154
	s_lshl_b64 s[10:11], s[10:11], 25
	s_add_u32 s10, s93, s10
	s_addc_u32 s11, s94, s11
	v_ashrrev_i32_e32 v193, 31, v192
	s_mov_b64 s[74:75], 0
	s_waitcnt vmcnt(0)
	v_xor_b32_e32 v3, 0x80000000, v3
	v_xor_b32_e32 v7, 0x80000000, v7
	v_xor_b32_e32 v6, 0x80000000, v6
	v_xor_b32_e32 v2, 0x80000000, v2
	v_pk_fma_f32 v[10:11], v[6:7], s[42:43], v[20:21] op_sel_hi:[1,0,0]
	v_pk_fma_f32 v[12:13], v[4:5], s[42:43], v[20:21] op_sel_hi:[1,0,0] neg_lo:[1,0,0] neg_hi:[1,0,0]
	v_pk_fma_f32 v[14:15], v[2:3], s[42:43], v[20:21] op_sel_hi:[1,0,0]
	global_load_dwordx4 v[6:9], v[18:19], off offset:528
	global_load_dwordx4 v[2:5], v[18:19], off offset:512
	v_pk_fma_f32 v[16:17], v[0:1], s[42:43], v[20:21] op_sel_hi:[1,0,0] neg_lo:[1,0,0] neg_hi:[1,0,0]
	v_pk_fma_f32 v[22:23], v[156:157], s[44:45], v[12:13] op_sel_hi:[1,0,1] neg_lo:[1,0,0] neg_hi:[1,0,0]
	v_pk_fma_f32 v[26:27], v[152:153], s[44:45], v[16:17] op_sel_hi:[1,0,1] neg_lo:[1,0,0] neg_hi:[1,0,0]
	v_exp_f32_e32 v22, v22
	v_exp_f32_e32 v23, v23
	v_exp_f32_e32 v26, v26
	v_pk_fma_f32 v[24:25], v[24:25], s[44:45], v[14:15] op_sel_hi:[1,0,1]
	v_add_f32_e32 v22, 0x3b808081, v22
	v_exp_f32_e32 v27, v27
	v_rcp_f32_e32 v22, v22
	v_add_f32_e32 v23, 0x3b808081, v23
	v_exp_f32_e32 v24, v24
	v_rcp_f32_e32 v23, v23
	v_exp_f32_e32 v25, v25
	v_add_f32_e32 v26, 0x3b808081, v26
	v_rcp_f32_e32 v26, v26
	v_add_f32_e32 v27, 0x3b808081, v27
	v_rcp_f32_e32 v27, v27
	v_add_f32_e32 v24, 0x3b808081, v24
	v_cvt_pk_u8_f32 v22, v22, 0, 0
	v_rcp_f32_e32 v24, v24
	v_add_f32_e32 v25, 0x3b808081, v25
	v_cvt_pk_u8_f32 v22, v23, 1, v22
	v_rcp_f32_e32 v25, v25
	v_lshl_add_u64 v[18:19], s[10:11], 0, v[178:179]
	v_pk_fma_f32 v[28:29], v[136:137], s[44:45], v[16:17] op_sel_hi:[1,0,1] neg_lo:[1,0,0] neg_hi:[1,0,0]
	s_mov_b64 s[10:11], 0x80000
	v_exp_f32_e32 v28, v28
	v_exp_f32_e32 v29, v29
	v_add_f32_e32 v28, 0x3b808081, v28
	v_rcp_f32_e32 v28, v28
	v_add_f32_e32 v29, 0x3b808081, v29
	v_rcp_f32_e32 v29, v29
	s_waitcnt vmcnt(1)
	v_pk_fma_f32 v[6:7], v[6:7], s[42:43], v[20:21] op_sel_hi:[1,0,0] neg_lo:[1,0,0] neg_hi:[1,0,0]
	s_waitcnt vmcnt(0)
	v_xor_b32_e32 v1, 0x80000000, v5
	v_xor_b32_e32 v0, 0x80000000, v4
	v_xor_b32_e32 v5, 0x80000000, v9
	v_xor_b32_e32 v4, 0x80000000, v8
	v_pk_fma_f32 v[0:1], v[0:1], s[42:43], v[20:21] op_sel_hi:[1,0,0]
	v_pk_fma_f32 v[2:3], v[2:3], s[42:43], v[20:21] op_sel_hi:[1,0,0] neg_lo:[1,0,0] neg_hi:[1,0,0]
	v_pk_fma_f32 v[4:5], v[4:5], s[42:43], v[20:21] op_sel_hi:[1,0,0]
	v_xor_b32_e32 v21, 0x80000000, v159
	v_xor_b32_e32 v20, 0x80000000, v158
	v_pk_fma_f32 v[20:21], v[20:21], s[44:45], v[10:11] op_sel_hi:[1,0,1]
	v_lshlrev_b64 v[8:9], 12, v[192:193]
	v_exp_f32_e32 v20, v20
	v_exp_f32_e32 v21, v21
	v_lshl_add_u64 v[8:9], v[18:19], 0, v[8:9]
	v_add_f32_e32 v20, 0x3b808081, v20
	v_rcp_f32_e32 v20, v20
	v_add_f32_e32 v21, 0x3b808081, v21
	v_rcp_f32_e32 v21, v21
	v_cvt_pk_u8_f32 v20, v20, 2, v22
	v_pk_fma_f32 v[22:23], v[148:149], s[44:45], v[2:3] op_sel_hi:[1,0,1] neg_lo:[1,0,0] neg_hi:[1,0,0]
	v_cvt_pk_u8_f32 v20, v21, 3, v20
	v_cvt_pk_u8_f32 v21, v26, 0, 0
	v_cvt_pk_u8_f32 v21, v27, 1, v21
	v_cvt_pk_u8_f32 v21, v24, 2, v21
	v_cvt_pk_u8_f32 v21, v25, 3, v21
	v_mov_b32_e32 v252, v253
	global_store_dwordx2 v252, v[20:21], s[100:101] nt
	v_xor_b32_e32 v21, 0x80000000, v151
	v_xor_b32_e32 v20, 0x80000000, v150
	v_exp_f32_e32 v22, v22
	v_pk_fma_f32 v[20:21], v[20:21], s[44:45], v[0:1] op_sel_hi:[1,0,1]
	v_exp_f32_e32 v23, v23
	v_pk_fma_f32 v[26:27], v[144:145], s[44:45], v[6:7] op_sel_hi:[1,0,1] neg_lo:[1,0,0] neg_hi:[1,0,0]
	v_exp_f32_e32 v20, v20
	v_xor_b32_e32 v25, 0x80000000, v147
	v_xor_b32_e32 v24, 0x80000000, v146
	v_exp_f32_e32 v26, v26
	v_exp_f32_e32 v21, v21
	v_pk_fma_f32 v[24:25], v[24:25], s[44:45], v[4:5] op_sel_hi:[1,0,1]
	v_add_f32_e32 v22, 0x3b808081, v22
	v_exp_f32_e32 v27, v27
	v_rcp_f32_e32 v22, v22
	v_add_f32_e32 v23, 0x3b808081, v23
	v_exp_f32_e32 v24, v24
	v_rcp_f32_e32 v23, v23
	v_add_f32_e32 v20, 0x3b808081, v20
	v_exp_f32_e32 v25, v25
	v_add_f32_e32 v26, 0x3b808081, v26
	v_rcp_f32_e32 v20, v20
	v_add_f32_e32 v21, 0x3b808081, v21
	v_rcp_f32_e32 v26, v26
	v_add_f32_e32 v27, 0x3b808081, v27
	v_rcp_f32_e32 v21, v21
	v_rcp_f32_e32 v27, v27
	v_add_f32_e32 v24, 0x3b808081, v24
	v_cvt_pk_u8_f32 v22, v22, 0, 0
	v_rcp_f32_e32 v24, v24
	v_add_f32_e32 v25, 0x3b808081, v25
	v_cvt_pk_u8_f32 v22, v23, 1, v22
	v_rcp_f32_e32 v25, v25
	v_cvt_pk_u8_f32 v20, v20, 2, v22
	v_cvt_pk_u8_f32 v20, v21, 3, v20
	v_cvt_pk_u8_f32 v21, v26, 0, 0
	v_cvt_pk_u8_f32 v21, v27, 1, v21
	v_cvt_pk_u8_f32 v21, v24, 2, v21
	v_cvt_pk_u8_f32 v21, v25, 3, v21
	v_pk_fma_f32 v[24:25], v[140:141], s[44:45], v[12:13] op_sel_hi:[1,0,1] neg_lo:[1,0,0] neg_hi:[1,0,0]
	v_xor_b32_e32 v23, 0x80000000, v143
	v_xor_b32_e32 v22, 0x80000000, v142
	v_exp_f32_e32 v24, v24
	v_pk_fma_f32 v[22:23], v[22:23], s[44:45], v[10:11] op_sel_hi:[1,0,1]
	v_exp_f32_e32 v25, v25
	v_exp_f32_e32 v22, v22
	v_xor_b32_e32 v27, 0x80000000, v139
	v_xor_b32_e32 v26, 0x80000000, v138
	v_exp_f32_e32 v23, v23
	v_pk_fma_f32 v[26:27], v[26:27], s[44:45], v[14:15] op_sel_hi:[1,0,1]
	v_add_f32_e32 v24, 0x3b808081, v24
	v_rcp_f32_e32 v24, v24
	v_add_f32_e32 v25, 0x3b808081, v25
	v_exp_f32_e32 v26, v26
	v_rcp_f32_e32 v25, v25
	v_add_f32_e32 v22, 0x3b808081, v22
	v_exp_f32_e32 v27, v27
	v_rcp_f32_e32 v22, v22
	v_add_f32_e32 v23, 0x3b808081, v23
	v_rcp_f32_e32 v23, v23
	v_add_f32_e32 v26, 0x3b808081, v26
	v_cvt_pk_u8_f32 v24, v24, 0, 0
	v_rcp_f32_e32 v26, v26
	v_add_f32_e32 v27, 0x3b808081, v27
	v_cvt_pk_u8_f32 v24, v25, 1, v24
	v_rcp_f32_e32 v27, v27
	v_cvt_pk_u8_f32 v22, v22, 2, v24
	v_add_u32_e32 v252, 0x200, v253
	global_store_dwordx2 v252, v[20:21], s[100:101] nt
	v_or_b32_e32 v20, 16, v192
	v_cvt_pk_u8_f32 v22, v23, 3, v22
	v_cvt_pk_u8_f32 v23, v28, 0, 0
	v_ashrrev_i32_e32 v21, 31, v20
	v_cvt_pk_u8_f32 v23, v29, 1, v23
	v_lshlrev_b64 v[20:21], 12, v[20:21]
	v_cvt_pk_u8_f32 v23, v26, 2, v23
	v_lshl_add_u64 v[20:21], v[18:19], 0, v[20:21]
	v_cvt_pk_u8_f32 v23, v27, 3, v23
	v_pk_fma_f32 v[24:25], v[132:133], s[44:45], v[2:3] op_sel_hi:[1,0,1] neg_lo:[1,0,0] neg_hi:[1,0,0]
	v_add_u32_e32 v252, 0x2000, v253
	global_store_dwordx2 v252, v[22:23], s[100:101] nt
	v_xor_b32_e32 v23, 0x80000000, v135
	v_xor_b32_e32 v22, 0x80000000, v134
	v_exp_f32_e32 v24, v24
	v_pk_fma_f32 v[22:23], v[22:23], s[44:45], v[0:1] op_sel_hi:[1,0,1]
	v_exp_f32_e32 v25, v25
	v_pk_fma_f32 v[28:29], v[128:129], s[44:45], v[6:7] op_sel_hi:[1,0,1] neg_lo:[1,0,0] neg_hi:[1,0,0]
	v_exp_f32_e32 v22, v22
	v_xor_b32_e32 v27, 0x80000000, v131
	v_xor_b32_e32 v26, 0x80000000, v130
	v_exp_f32_e32 v28, v28
	v_exp_f32_e32 v23, v23
	v_pk_fma_f32 v[26:27], v[26:27], s[44:45], v[4:5] op_sel_hi:[1,0,1]
	v_add_f32_e32 v24, 0x3b808081, v24
	v_exp_f32_e32 v29, v29
	v_rcp_f32_e32 v24, v24
	v_add_f32_e32 v25, 0x3b808081, v25
	v_exp_f32_e32 v26, v26
	v_rcp_f32_e32 v25, v25
	v_add_f32_e32 v22, 0x3b808081, v22
	v_exp_f32_e32 v27, v27
	v_add_f32_e32 v28, 0x3b808081, v28
	v_rcp_f32_e32 v22, v22
	v_add_f32_e32 v23, 0x3b808081, v23
	v_rcp_f32_e32 v28, v28
	v_add_f32_e32 v29, 0x3b808081, v29
	v_rcp_f32_e32 v23, v23
	v_rcp_f32_e32 v29, v29
	v_add_f32_e32 v26, 0x3b808081, v26
	v_cvt_pk_u8_f32 v24, v24, 0, 0
	v_rcp_f32_e32 v26, v26
	v_add_f32_e32 v27, 0x3b808081, v27
	v_cvt_pk_u8_f32 v24, v25, 1, v24
	v_rcp_f32_e32 v27, v27
	v_cvt_pk_u8_f32 v22, v22, 2, v24
	v_cvt_pk_u8_f32 v22, v23, 3, v22
	v_cvt_pk_u8_f32 v23, v28, 0, 0
	v_cvt_pk_u8_f32 v23, v29, 1, v23
	v_cvt_pk_u8_f32 v23, v26, 2, v23
	v_cvt_pk_u8_f32 v23, v27, 3, v23
	v_pk_fma_f32 v[24:25], v[124:125], s[44:45], v[12:13] op_sel_hi:[1,0,1] neg_lo:[1,0,0] neg_hi:[1,0,0]
	v_add_u32_e32 v252, 0x2200, v253
	global_store_dwordx2 v252, v[22:23], s[100:101] nt
	v_xor_b32_e32 v23, 0x80000000, v127
	v_xor_b32_e32 v22, 0x80000000, v126
	v_exp_f32_e32 v24, v24
	v_pk_fma_f32 v[22:23], v[22:23], s[44:45], v[10:11] op_sel_hi:[1,0,1]
	v_exp_f32_e32 v25, v25
	v_pk_fma_f32 v[28:29], v[120:121], s[44:45], v[16:17] op_sel_hi:[1,0,1] neg_lo:[1,0,0] neg_hi:[1,0,0]
	v_exp_f32_e32 v22, v22
	v_xor_b32_e32 v27, 0x80000000, v123
	v_xor_b32_e32 v26, 0x80000000, v122
	v_exp_f32_e32 v28, v28
	v_exp_f32_e32 v23, v23
	v_pk_fma_f32 v[26:27], v[26:27], s[44:45], v[14:15] op_sel_hi:[1,0,1]
	v_add_f32_e32 v24, 0x3b808081, v24
	v_exp_f32_e32 v29, v29
	v_rcp_f32_e32 v24, v24
	v_add_f32_e32 v25, 0x3b808081, v25
	v_exp_f32_e32 v26, v26
	v_rcp_f32_e32 v25, v25
	v_add_f32_e32 v22, 0x3b808081, v22
	v_exp_f32_e32 v27, v27
	v_add_f32_e32 v28, 0x3b808081, v28
	v_rcp_f32_e32 v22, v22
	v_add_f32_e32 v23, 0x3b808081, v23
	v_rcp_f32_e32 v28, v28
	v_add_f32_e32 v29, 0x3b808081, v29
	v_rcp_f32_e32 v23, v23
	v_rcp_f32_e32 v29, v29
	v_add_f32_e32 v26, 0x3b808081, v26
	v_cvt_pk_u8_f32 v24, v24, 0, 0
	v_rcp_f32_e32 v26, v26
	v_add_f32_e32 v27, 0x3b808081, v27
	v_cvt_pk_u8_f32 v24, v25, 1, v24
	v_rcp_f32_e32 v27, v27
	v_cvt_pk_u8_f32 v22, v22, 2, v24
	v_or_b32_e32 v20, 32, v192
	v_cvt_pk_u8_f32 v22, v23, 3, v22
	v_cvt_pk_u8_f32 v23, v28, 0, 0
	v_ashrrev_i32_e32 v21, 31, v20
	v_cvt_pk_u8_f32 v23, v29, 1, v23
	v_lshlrev_b64 v[20:21], 12, v[20:21]
	v_cvt_pk_u8_f32 v23, v26, 2, v23
	v_lshl_add_u64 v[20:21], v[18:19], 0, v[20:21]
	v_cvt_pk_u8_f32 v23, v27, 3, v23
	v_pk_fma_f32 v[24:25], v[116:117], s[44:45], v[2:3] op_sel_hi:[1,0,1] neg_lo:[1,0,0] neg_hi:[1,0,0]
	v_add_u32_e32 v252, 0x4000, v253
	global_store_dwordx2 v252, v[22:23], s[100:101] nt
	v_xor_b32_e32 v23, 0x80000000, v119
	v_xor_b32_e32 v22, 0x80000000, v118
	v_exp_f32_e32 v24, v24
	v_pk_fma_f32 v[22:23], v[22:23], s[44:45], v[0:1] op_sel_hi:[1,0,1]
	v_exp_f32_e32 v25, v25
	v_pk_fma_f32 v[28:29], v[112:113], s[44:45], v[6:7] op_sel_hi:[1,0,1] neg_lo:[1,0,0] neg_hi:[1,0,0]
	v_exp_f32_e32 v22, v22
	v_xor_b32_e32 v27, 0x80000000, v115
	v_xor_b32_e32 v26, 0x80000000, v114
	v_exp_f32_e32 v28, v28
	v_exp_f32_e32 v23, v23
	v_pk_fma_f32 v[26:27], v[26:27], s[44:45], v[4:5] op_sel_hi:[1,0,1]
	v_add_f32_e32 v24, 0x3b808081, v24
	v_exp_f32_e32 v29, v29
	v_rcp_f32_e32 v24, v24
	v_add_f32_e32 v25, 0x3b808081, v25
	v_exp_f32_e32 v26, v26
	v_rcp_f32_e32 v25, v25
	v_add_f32_e32 v22, 0x3b808081, v22
	v_exp_f32_e32 v27, v27
	v_add_f32_e32 v28, 0x3b808081, v28
	v_rcp_f32_e32 v22, v22
	v_add_f32_e32 v23, 0x3b808081, v23
	v_rcp_f32_e32 v28, v28
	v_add_f32_e32 v29, 0x3b808081, v29
	v_rcp_f32_e32 v23, v23
	v_rcp_f32_e32 v29, v29
	v_add_f32_e32 v26, 0x3b808081, v26
	v_cvt_pk_u8_f32 v24, v24, 0, 0
	v_rcp_f32_e32 v26, v26
	v_add_f32_e32 v27, 0x3b808081, v27
	v_cvt_pk_u8_f32 v24, v25, 1, v24
	v_rcp_f32_e32 v27, v27
	v_cvt_pk_u8_f32 v22, v22, 2, v24
	v_cvt_pk_u8_f32 v22, v23, 3, v22
	v_cvt_pk_u8_f32 v23, v28, 0, 0
	v_cvt_pk_u8_f32 v23, v29, 1, v23
	v_cvt_pk_u8_f32 v23, v26, 2, v23
	v_cvt_pk_u8_f32 v23, v27, 3, v23
	v_add_u32_e32 v252, 0x4200, v253
	global_store_dwordx2 v252, v[22:23], s[100:101] nt
	v_or_b32_e32 v20, 48, v192
	v_ashrrev_i32_e32 v21, 31, v20
	v_lshlrev_b64 v[20:21], 12, v[20:21]
	v_pk_fma_f32 v[22:23], v[108:109], s[44:45], v[12:13] op_sel_hi:[1,0,1] neg_lo:[1,0,0] neg_hi:[1,0,0]
	v_lshl_add_u64 v[18:19], v[18:19], 0, v[20:21]
	v_xor_b32_e32 v21, 0x80000000, v111
	v_xor_b32_e32 v20, 0x80000000, v110
	v_exp_f32_e32 v22, v22
	v_pk_fma_f32 v[20:21], v[20:21], s[44:45], v[10:11] op_sel_hi:[1,0,1]
	v_exp_f32_e32 v23, v23
	v_pk_fma_f32 v[26:27], v[104:105], s[44:45], v[16:17] op_sel_hi:[1,0,1] neg_lo:[1,0,0] neg_hi:[1,0,0]
	v_exp_f32_e32 v20, v20
	v_xor_b32_e32 v25, 0x80000000, v107
	v_xor_b32_e32 v24, 0x80000000, v106
	v_exp_f32_e32 v26, v26
	v_exp_f32_e32 v21, v21
	v_pk_fma_f32 v[24:25], v[24:25], s[44:45], v[14:15] op_sel_hi:[1,0,1]
	v_add_f32_e32 v22, 0x3b808081, v22
	v_exp_f32_e32 v27, v27
	v_rcp_f32_e32 v22, v22
	v_add_f32_e32 v23, 0x3b808081, v23
	v_exp_f32_e32 v24, v24
	v_rcp_f32_e32 v23, v23
	v_add_f32_e32 v20, 0x3b808081, v20
	v_exp_f32_e32 v25, v25
	v_add_f32_e32 v26, 0x3b808081, v26
	v_rcp_f32_e32 v20, v20
	v_add_f32_e32 v21, 0x3b808081, v21
	v_rcp_f32_e32 v26, v26
	v_add_f32_e32 v27, 0x3b808081, v27
	v_rcp_f32_e32 v21, v21
	v_rcp_f32_e32 v27, v27
	v_add_f32_e32 v24, 0x3b808081, v24
	v_cvt_pk_u8_f32 v22, v22, 0, 0
	v_rcp_f32_e32 v24, v24
	v_add_f32_e32 v25, 0x3b808081, v25
	v_cvt_pk_u8_f32 v22, v23, 1, v22
	v_rcp_f32_e32 v25, v25
	v_cvt_pk_u8_f32 v20, v20, 2, v22
	v_cvt_pk_u8_f32 v20, v21, 3, v20
	v_cvt_pk_u8_f32 v21, v26, 0, 0
	v_cvt_pk_u8_f32 v21, v27, 1, v21
	v_cvt_pk_u8_f32 v21, v24, 2, v21
	v_cvt_pk_u8_f32 v21, v25, 3, v21
	v_pk_fma_f32 v[22:23], v[100:101], s[44:45], v[2:3] op_sel_hi:[1,0,1] neg_lo:[1,0,0] neg_hi:[1,0,0]
	v_add_u32_e32 v252, 0x6000, v253
	global_store_dwordx2 v252, v[20:21], s[100:101] nt
	v_xor_b32_e32 v21, 0x80000000, v103
	v_xor_b32_e32 v20, 0x80000000, v102
	v_exp_f32_e32 v22, v22
	v_pk_fma_f32 v[20:21], v[20:21], s[44:45], v[0:1] op_sel_hi:[1,0,1]
	v_exp_f32_e32 v23, v23
	v_pk_fma_f32 v[26:27], v[96:97], s[44:45], v[6:7] op_sel_hi:[1,0,1] neg_lo:[1,0,0] neg_hi:[1,0,0]
	v_exp_f32_e32 v20, v20
	v_xor_b32_e32 v25, 0x80000000, v99
	v_xor_b32_e32 v24, 0x80000000, v98
	v_exp_f32_e32 v26, v26
	v_exp_f32_e32 v21, v21
	v_pk_fma_f32 v[24:25], v[24:25], s[44:45], v[4:5] op_sel_hi:[1,0,1]
	v_add_f32_e32 v22, 0x3b808081, v22
	v_exp_f32_e32 v27, v27
	v_rcp_f32_e32 v22, v22
	v_add_f32_e32 v23, 0x3b808081, v23
	v_exp_f32_e32 v24, v24
	v_rcp_f32_e32 v23, v23
	v_add_f32_e32 v20, 0x3b808081, v20
	v_exp_f32_e32 v25, v25
	v_add_f32_e32 v26, 0x3b808081, v26
	v_rcp_f32_e32 v20, v20
	v_add_f32_e32 v21, 0x3b808081, v21
	v_rcp_f32_e32 v26, v26
	v_add_f32_e32 v27, 0x3b808081, v27
	v_rcp_f32_e32 v21, v21
	v_rcp_f32_e32 v27, v27
	v_add_f32_e32 v24, 0x3b808081, v24
	v_cvt_pk_u8_f32 v22, v22, 0, 0
	v_rcp_f32_e32 v24, v24
	v_add_f32_e32 v25, 0x3b808081, v25
	v_cvt_pk_u8_f32 v22, v23, 1, v22
	v_rcp_f32_e32 v25, v25
	v_cvt_pk_u8_f32 v20, v20, 2, v22
	v_cvt_pk_u8_f32 v20, v21, 3, v20
	v_cvt_pk_u8_f32 v21, v26, 0, 0
	v_cvt_pk_u8_f32 v21, v27, 1, v21
	v_cvt_pk_u8_f32 v21, v24, 2, v21
	v_cvt_pk_u8_f32 v21, v25, 3, v21
	v_pk_fma_f32 v[22:23], v[92:93], s[44:45], v[12:13] op_sel_hi:[1,0,1] neg_lo:[1,0,0] neg_hi:[1,0,0]
	v_add_u32_e32 v252, 0x6200, v253
	global_store_dwordx2 v252, v[20:21], s[100:101] nt
	v_xor_b32_e32 v21, 0x80000000, v95
	v_xor_b32_e32 v20, 0x80000000, v94
	v_exp_f32_e32 v22, v22
	v_pk_fma_f32 v[20:21], v[20:21], s[44:45], v[10:11] op_sel_hi:[1,0,1]
	v_exp_f32_e32 v23, v23
	v_pk_fma_f32 v[26:27], v[88:89], s[44:45], v[16:17] op_sel_hi:[1,0,1] neg_lo:[1,0,0] neg_hi:[1,0,0]
	v_exp_f32_e32 v20, v20
	v_xor_b32_e32 v25, 0x80000000, v91
	v_xor_b32_e32 v24, 0x80000000, v90
	v_exp_f32_e32 v26, v26
	v_exp_f32_e32 v21, v21
	v_pk_fma_f32 v[24:25], v[24:25], s[44:45], v[14:15] op_sel_hi:[1,0,1]
	v_add_f32_e32 v22, 0x3b808081, v22
	v_exp_f32_e32 v27, v27
	v_rcp_f32_e32 v22, v22
	v_add_f32_e32 v23, 0x3b808081, v23
	v_exp_f32_e32 v24, v24
	v_rcp_f32_e32 v23, v23
	v_add_f32_e32 v20, 0x3b808081, v20
	v_exp_f32_e32 v25, v25
	v_add_f32_e32 v26, 0x3b808081, v26
	v_rcp_f32_e32 v20, v20
	v_add_f32_e32 v21, 0x3b808081, v21
	v_rcp_f32_e32 v26, v26
	v_add_f32_e32 v27, 0x3b808081, v27
	v_rcp_f32_e32 v21, v21
	v_rcp_f32_e32 v27, v27
	v_add_f32_e32 v24, 0x3b808081, v24
	v_cvt_pk_u8_f32 v22, v22, 0, 0
	v_rcp_f32_e32 v24, v24
	v_add_f32_e32 v25, 0x3b808081, v25
	v_cvt_pk_u8_f32 v22, v23, 1, v22
	v_rcp_f32_e32 v25, v25
	v_cvt_pk_u8_f32 v20, v20, 2, v22
	v_cvt_pk_u8_f32 v20, v21, 3, v20
	v_cvt_pk_u8_f32 v21, v26, 0, 0
	v_lshl_add_u64 v[18:19], v[8:9], 0, s[10:11]
	v_cvt_pk_u8_f32 v21, v27, 1, v21
	s_mov_b32 s10, 0x80000
	v_cvt_pk_u8_f32 v21, v24, 2, v21
	v_add_co_u32_e32 v22, vcc, s10, v8
	v_cvt_pk_u8_f32 v21, v25, 3, v21
	s_nop 0
	v_addc_co_u32_e32 v23, vcc, 0, v9, vcc
	v_add_u32_e32 v252, 0x8000, v253
	global_store_dwordx2 v252, v[20:21], s[100:101] nt
	v_pk_fma_f32 v[22:23], v[84:85], s[44:45], v[2:3] op_sel_hi:[1,0,1] neg_lo:[1,0,0] neg_hi:[1,0,0]
	v_xor_b32_e32 v21, 0x80000000, v87
	v_xor_b32_e32 v20, 0x80000000, v86
	v_exp_f32_e32 v22, v22
	v_pk_fma_f32 v[20:21], v[20:21], s[44:45], v[0:1] op_sel_hi:[1,0,1]
	v_exp_f32_e32 v23, v23
	v_pk_fma_f32 v[26:27], v[80:81], s[44:45], v[6:7] op_sel_hi:[1,0,1] neg_lo:[1,0,0] neg_hi:[1,0,0]
	v_exp_f32_e32 v20, v20
	v_xor_b32_e32 v25, 0x80000000, v83
	v_xor_b32_e32 v24, 0x80000000, v82
	v_exp_f32_e32 v26, v26
	v_exp_f32_e32 v21, v21
	v_pk_fma_f32 v[24:25], v[24:25], s[44:45], v[4:5] op_sel_hi:[1,0,1]
	v_add_f32_e32 v22, 0x3b808081, v22
	v_exp_f32_e32 v27, v27
	v_rcp_f32_e32 v22, v22
	v_add_f32_e32 v23, 0x3b808081, v23
	v_exp_f32_e32 v24, v24
	v_rcp_f32_e32 v23, v23
	v_add_f32_e32 v20, 0x3b808081, v20
	v_exp_f32_e32 v25, v25
	v_add_f32_e32 v26, 0x3b808081, v26
	v_rcp_f32_e32 v20, v20
	v_add_f32_e32 v21, 0x3b808081, v21
	v_rcp_f32_e32 v26, v26
	v_add_f32_e32 v27, 0x3b808081, v27
	v_rcp_f32_e32 v21, v21
	v_rcp_f32_e32 v27, v27
	v_add_f32_e32 v24, 0x3b808081, v24
	v_cvt_pk_u8_f32 v22, v22, 0, 0
	v_rcp_f32_e32 v24, v24
	v_add_f32_e32 v25, 0x3b808081, v25
	v_cvt_pk_u8_f32 v22, v23, 1, v22
	v_rcp_f32_e32 v25, v25
	v_cvt_pk_u8_f32 v20, v20, 2, v22
	v_cvt_pk_u8_f32 v20, v21, 3, v20
	v_cvt_pk_u8_f32 v21, v26, 0, 0
	v_cvt_pk_u8_f32 v21, v27, 1, v21
	v_cvt_pk_u8_f32 v21, v24, 2, v21
	v_cvt_pk_u8_f32 v21, v25, 3, v21
	v_pk_fma_f32 v[22:23], v[76:77], s[44:45], v[12:13] op_sel_hi:[1,0,1] neg_lo:[1,0,0] neg_hi:[1,0,0]
	v_add_u32_e32 v252, 0x8200, v253
	global_store_dwordx2 v252, v[20:21], s[100:101] nt
	v_xor_b32_e32 v21, 0x80000000, v79
	v_xor_b32_e32 v20, 0x80000000, v78
	v_exp_f32_e32 v22, v22
	v_pk_fma_f32 v[20:21], v[20:21], s[44:45], v[10:11] op_sel_hi:[1,0,1]
	v_exp_f32_e32 v23, v23
	v_pk_fma_f32 v[26:27], v[72:73], s[44:45], v[16:17] op_sel_hi:[1,0,1] neg_lo:[1,0,0] neg_hi:[1,0,0]
	v_exp_f32_e32 v20, v20
	v_xor_b32_e32 v25, 0x80000000, v75
	v_xor_b32_e32 v24, 0x80000000, v74
	v_exp_f32_e32 v26, v26
	v_exp_f32_e32 v21, v21
	v_pk_fma_f32 v[24:25], v[24:25], s[44:45], v[14:15] op_sel_hi:[1,0,1]
	v_add_f32_e32 v22, 0x3b808081, v22
	v_exp_f32_e32 v27, v27
	v_rcp_f32_e32 v22, v22
	v_add_f32_e32 v23, 0x3b808081, v23
	v_exp_f32_e32 v24, v24
	v_rcp_f32_e32 v23, v23
	v_add_f32_e32 v20, 0x3b808081, v20
	v_exp_f32_e32 v25, v25
	v_add_f32_e32 v26, 0x3b808081, v26
	v_rcp_f32_e32 v20, v20
	v_add_f32_e32 v21, 0x3b808081, v21
	v_rcp_f32_e32 v26, v26
	v_add_f32_e32 v27, 0x3b808081, v27
	v_rcp_f32_e32 v21, v21
	v_rcp_f32_e32 v27, v27
	v_add_f32_e32 v24, 0x3b808081, v24
	v_cvt_pk_u8_f32 v22, v22, 0, 0
	v_rcp_f32_e32 v24, v24
	v_add_f32_e32 v25, 0x3b808081, v25
	v_cvt_pk_u8_f32 v22, v23, 1, v22
	v_rcp_f32_e32 v25, v25
	v_cvt_pk_u8_f32 v20, v20, 2, v22
	s_mov_b64 s[10:11], 0x90000
	v_cvt_pk_u8_f32 v20, v21, 3, v20
	v_cvt_pk_u8_f32 v21, v26, 0, 0
	v_lshl_add_u64 v[18:19], v[8:9], 0, s[10:11]
	v_cvt_pk_u8_f32 v21, v27, 1, v21
	s_mov_b32 s10, 0x90000
	v_cvt_pk_u8_f32 v21, v24, 2, v21
	v_add_co_u32_e32 v22, vcc, s10, v8
	v_cvt_pk_u8_f32 v21, v25, 3, v21
	s_nop 0
	v_addc_co_u32_e32 v23, vcc, 0, v9, vcc
	v_add_u32_e32 v252, 0xa000, v253
	global_store_dwordx2 v252, v[20:21], s[100:101] nt
	v_pk_fma_f32 v[22:23], v[68:69], s[44:45], v[2:3] op_sel_hi:[1,0,1] neg_lo:[1,0,0] neg_hi:[1,0,0]
	v_xor_b32_e32 v21, 0x80000000, v71
	v_xor_b32_e32 v20, 0x80000000, v70
	v_exp_f32_e32 v22, v22
	v_pk_fma_f32 v[20:21], v[20:21], s[44:45], v[0:1] op_sel_hi:[1,0,1]
	v_exp_f32_e32 v23, v23
	v_pk_fma_f32 v[26:27], v[64:65], s[44:45], v[6:7] op_sel_hi:[1,0,1] neg_lo:[1,0,0] neg_hi:[1,0,0]
	v_exp_f32_e32 v20, v20
	v_xor_b32_e32 v25, 0x80000000, v67
	v_xor_b32_e32 v24, 0x80000000, v66
	v_exp_f32_e32 v26, v26
	v_exp_f32_e32 v21, v21
	v_pk_fma_f32 v[24:25], v[24:25], s[44:45], v[4:5] op_sel_hi:[1,0,1]
	v_add_f32_e32 v22, 0x3b808081, v22
	v_exp_f32_e32 v27, v27
	v_rcp_f32_e32 v22, v22
	v_add_f32_e32 v23, 0x3b808081, v23
	v_exp_f32_e32 v24, v24
	v_rcp_f32_e32 v23, v23
	v_add_f32_e32 v20, 0x3b808081, v20
	v_exp_f32_e32 v25, v25
	v_add_f32_e32 v26, 0x3b808081, v26
	v_rcp_f32_e32 v20, v20
	v_add_f32_e32 v21, 0x3b808081, v21
	v_rcp_f32_e32 v26, v26
	v_add_f32_e32 v27, 0x3b808081, v27
	v_rcp_f32_e32 v21, v21
	v_rcp_f32_e32 v27, v27
	v_add_f32_e32 v24, 0x3b808081, v24
	v_cvt_pk_u8_f32 v22, v22, 0, 0
	v_rcp_f32_e32 v24, v24
	v_add_f32_e32 v25, 0x3b808081, v25
	v_cvt_pk_u8_f32 v22, v23, 1, v22
	v_rcp_f32_e32 v25, v25
	v_cvt_pk_u8_f32 v20, v20, 2, v22
	v_cvt_pk_u8_f32 v20, v21, 3, v20
	v_cvt_pk_u8_f32 v21, v26, 0, 0
	v_cvt_pk_u8_f32 v21, v27, 1, v21
	v_cvt_pk_u8_f32 v21, v24, 2, v21
	v_cvt_pk_u8_f32 v21, v25, 3, v21
	v_pk_fma_f32 v[22:23], v[60:61], s[44:45], v[12:13] op_sel_hi:[1,0,1] neg_lo:[1,0,0] neg_hi:[1,0,0]
	v_add_u32_e32 v252, 0xa200, v253
	global_store_dwordx2 v252, v[20:21], s[100:101] nt
	v_xor_b32_e32 v21, 0x80000000, v63
	v_xor_b32_e32 v20, 0x80000000, v62
	v_exp_f32_e32 v22, v22
	v_pk_fma_f32 v[20:21], v[20:21], s[44:45], v[10:11] op_sel_hi:[1,0,1]
	v_exp_f32_e32 v23, v23
	v_pk_fma_f32 v[26:27], v[56:57], s[44:45], v[16:17] op_sel_hi:[1,0,1] neg_lo:[1,0,0] neg_hi:[1,0,0]
	v_exp_f32_e32 v20, v20
	v_xor_b32_e32 v25, 0x80000000, v59
	v_xor_b32_e32 v24, 0x80000000, v58
	v_exp_f32_e32 v26, v26
	v_exp_f32_e32 v21, v21
	v_pk_fma_f32 v[24:25], v[24:25], s[44:45], v[14:15] op_sel_hi:[1,0,1]
	v_add_f32_e32 v22, 0x3b808081, v22
	v_exp_f32_e32 v27, v27
	v_rcp_f32_e32 v22, v22
	v_add_f32_e32 v23, 0x3b808081, v23
	v_exp_f32_e32 v24, v24
	v_rcp_f32_e32 v23, v23
	v_add_f32_e32 v20, 0x3b808081, v20
	v_exp_f32_e32 v25, v25
	v_add_f32_e32 v26, 0x3b808081, v26
	v_rcp_f32_e32 v20, v20
	v_add_f32_e32 v21, 0x3b808081, v21
	v_rcp_f32_e32 v26, v26
	v_add_f32_e32 v27, 0x3b808081, v27
	v_rcp_f32_e32 v21, v21
	v_rcp_f32_e32 v27, v27
	v_add_f32_e32 v24, 0x3b808081, v24
	v_cvt_pk_u8_f32 v22, v22, 0, 0
	v_rcp_f32_e32 v24, v24
	v_add_f32_e32 v25, 0x3b808081, v25
	v_cvt_pk_u8_f32 v22, v23, 1, v22
	v_rcp_f32_e32 v25, v25
	v_cvt_pk_u8_f32 v20, v20, 2, v22
	v_cvt_pk_u8_f32 v20, v21, 3, v20
	v_cvt_pk_u8_f32 v21, v26, 0, 0
	v_cvt_pk_u8_f32 v21, v27, 1, v21
	v_cvt_pk_u8_f32 v21, v24, 2, v21
	v_add_co_u32_e32 v22, vcc, s47, v8
	v_cvt_pk_u8_f32 v21, v25, 3, v21
	s_nop 0
	v_addc_co_u32_e32 v23, vcc, 0, v9, vcc
	v_add_u32_e32 v252, 0xc000, v253
	global_store_dwordx2 v252, v[20:21], s[100:101] nt
	v_pk_fma_f32 v[22:23], v[52:53], s[44:45], v[2:3] op_sel_hi:[1,0,1] neg_lo:[1,0,0] neg_hi:[1,0,0]
	v_xor_b32_e32 v21, 0x80000000, v55
	v_xor_b32_e32 v20, 0x80000000, v54
	v_exp_f32_e32 v22, v22
	v_pk_fma_f32 v[20:21], v[20:21], s[44:45], v[0:1] op_sel_hi:[1,0,1]
	v_exp_f32_e32 v23, v23
	v_pk_fma_f32 v[26:27], v[48:49], s[44:45], v[6:7] op_sel_hi:[1,0,1] neg_lo:[1,0,0] neg_hi:[1,0,0]
	v_exp_f32_e32 v20, v20
	v_xor_b32_e32 v25, 0x80000000, v51
	v_xor_b32_e32 v24, 0x80000000, v50
	v_exp_f32_e32 v26, v26
	v_exp_f32_e32 v21, v21
	v_pk_fma_f32 v[24:25], v[24:25], s[44:45], v[4:5] op_sel_hi:[1,0,1]
	v_add_f32_e32 v22, 0x3b808081, v22
	v_exp_f32_e32 v27, v27
	v_rcp_f32_e32 v22, v22
	v_add_f32_e32 v23, 0x3b808081, v23
	v_exp_f32_e32 v24, v24
	v_rcp_f32_e32 v23, v23
	v_add_f32_e32 v20, 0x3b808081, v20
	v_exp_f32_e32 v25, v25
	v_add_f32_e32 v26, 0x3b808081, v26
	v_rcp_f32_e32 v20, v20
	v_add_f32_e32 v21, 0x3b808081, v21
	v_rcp_f32_e32 v26, v26
	v_add_f32_e32 v27, 0x3b808081, v27
	v_rcp_f32_e32 v21, v21
	v_rcp_f32_e32 v27, v27
	v_add_f32_e32 v24, 0x3b808081, v24
	v_cvt_pk_u8_f32 v22, v22, 0, 0
	v_rcp_f32_e32 v24, v24
	v_add_f32_e32 v25, 0x3b808081, v25
	v_cvt_pk_u8_f32 v22, v23, 1, v22
	v_rcp_f32_e32 v25, v25
	v_cvt_pk_u8_f32 v20, v20, 2, v22
	v_cvt_pk_u8_f32 v20, v21, 3, v20
	v_cvt_pk_u8_f32 v21, v26, 0, 0
	v_cvt_pk_u8_f32 v21, v27, 1, v21
	v_cvt_pk_u8_f32 v21, v24, 2, v21
	v_lshl_add_u64 v[18:19], v[8:9], 0, s[50:51]
	v_cvt_pk_u8_f32 v21, v25, 3, v21
	v_pk_fma_f32 v[12:13], v[44:45], s[44:45], v[12:13] op_sel_hi:[1,0,1] neg_lo:[1,0,0] neg_hi:[1,0,0]
	v_add_u32_e32 v252, 0xc200, v253
	global_store_dwordx2 v252, v[20:21], s[100:101] nt
	v_xor_b32_e32 v21, 0x80000000, v47
	v_xor_b32_e32 v20, 0x80000000, v46
	v_exp_f32_e32 v12, v12
	v_pk_fma_f32 v[10:11], v[20:21], s[44:45], v[10:11] op_sel_hi:[1,0,1]
	v_exp_f32_e32 v13, v13
	v_pk_fma_f32 v[16:17], v[40:41], s[44:45], v[16:17] op_sel_hi:[1,0,1] neg_lo:[1,0,0] neg_hi:[1,0,0]
	v_exp_f32_e32 v10, v10
	v_xor_b32_e32 v21, 0x80000000, v43
	v_xor_b32_e32 v20, 0x80000000, v42
	v_exp_f32_e32 v16, v16
	v_exp_f32_e32 v11, v11
	v_pk_fma_f32 v[14:15], v[20:21], s[44:45], v[14:15] op_sel_hi:[1,0,1]
	v_add_f32_e32 v12, 0x3b808081, v12
	v_exp_f32_e32 v17, v17
	v_rcp_f32_e32 v12, v12
	v_add_f32_e32 v13, 0x3b808081, v13
	v_exp_f32_e32 v14, v14
	v_rcp_f32_e32 v13, v13
	v_add_f32_e32 v10, 0x3b808081, v10
	v_exp_f32_e32 v15, v15
	v_add_f32_e32 v16, 0x3b808081, v16
	v_rcp_f32_e32 v10, v10
	v_add_f32_e32 v11, 0x3b808081, v11
	v_rcp_f32_e32 v16, v16
	v_add_f32_e32 v17, 0x3b808081, v17
	v_rcp_f32_e32 v11, v11
	v_rcp_f32_e32 v17, v17
	v_add_f32_e32 v14, 0x3b808081, v14
	v_cvt_pk_u8_f32 v12, v12, 0, 0
	v_rcp_f32_e32 v14, v14
	v_add_f32_e32 v15, 0x3b808081, v15
	v_cvt_pk_u8_f32 v12, v13, 1, v12
	v_rcp_f32_e32 v15, v15
	v_cvt_pk_u8_f32 v10, v10, 2, v12
	v_cvt_pk_u8_f32 v10, v11, 3, v10
	v_cvt_pk_u8_f32 v11, v16, 0, 0
	v_cvt_pk_u8_f32 v11, v17, 1, v11
	v_lshl_add_u64 v[18:19], v[8:9], 0, s[52:53]
	v_cvt_pk_u8_f32 v11, v14, 2, v11
	v_add_co_u32_e32 v8, vcc, s5, v8
	v_cvt_pk_u8_f32 v11, v15, 3, v11
	s_nop 0
	v_addc_co_u32_e32 v9, vcc, 0, v9, vcc
	v_pk_fma_f32 v[2:3], v[36:37], s[44:45], v[2:3] op_sel_hi:[1,0,1] neg_lo:[1,0,0] neg_hi:[1,0,0]
	v_add_u32_e32 v252, 0xe000, v253
	global_store_dwordx2 v252, v[10:11], s[100:101] nt
	v_xor_b32_e32 v9, 0x80000000, v39
	v_xor_b32_e32 v8, 0x80000000, v38
	v_exp_f32_e32 v2, v2
	v_pk_fma_f32 v[0:1], v[8:9], s[44:45], v[0:1] op_sel_hi:[1,0,1]
	v_exp_f32_e32 v3, v3
	v_pk_fma_f32 v[6:7], v[32:33], s[44:45], v[6:7] op_sel_hi:[1,0,1] neg_lo:[1,0,0] neg_hi:[1,0,0]
	v_exp_f32_e32 v0, v0
	v_xor_b32_e32 v9, 0x80000000, v35
	v_xor_b32_e32 v8, 0x80000000, v34
	v_exp_f32_e32 v6, v6
	v_exp_f32_e32 v1, v1
	v_pk_fma_f32 v[4:5], v[8:9], s[44:45], v[4:5] op_sel_hi:[1,0,1]
	v_add_f32_e32 v2, 0x3b808081, v2
	v_exp_f32_e32 v7, v7
	v_rcp_f32_e32 v2, v2
	v_add_f32_e32 v3, 0x3b808081, v3
	v_exp_f32_e32 v4, v4
	v_rcp_f32_e32 v3, v3
	v_add_f32_e32 v0, 0x3b808081, v0
	v_exp_f32_e32 v5, v5
	v_add_f32_e32 v6, 0x3b808081, v6
	v_rcp_f32_e32 v0, v0
	v_add_f32_e32 v1, 0x3b808081, v1
	v_rcp_f32_e32 v6, v6
	v_add_f32_e32 v7, 0x3b808081, v7
	v_rcp_f32_e32 v1, v1
	v_rcp_f32_e32 v7, v7
	v_add_f32_e32 v4, 0x3b808081, v4
	v_cvt_pk_u8_f32 v2, v2, 0, 0
	v_rcp_f32_e32 v4, v4
	v_add_f32_e32 v5, 0x3b808081, v5
	v_cvt_pk_u8_f32 v2, v3, 1, v2
	v_rcp_f32_e32 v5, v5
	v_cvt_pk_u8_f32 v0, v0, 2, v2
	v_cvt_pk_u8_f32 v0, v1, 3, v0
	v_cvt_pk_u8_f32 v1, v6, 0, 0
	v_cvt_pk_u8_f32 v1, v7, 1, v1
	v_cvt_pk_u8_f32 v1, v4, 2, v1
	v_cvt_pk_u8_f32 v1, v5, 3, v1
	v_add_u32_e32 v252, 0xe200, v253
	global_store_dwordx2 v252, v[0:1], s[100:101] nt

.LBB0_342:
	s_ashr_i32 s19, s18, 31
	s_lshl_b64 s[28:29], s[18:19], 18
	s_add_u32 s28, s4, s28
	s_addc_u32 s29, s5, s29
	s_and_b64 s[8:9], s[8:9], exec
	s_cselect_b32 s19, s29, s43
	s_cselect_b32 s21, s28, s42
	s_ashr_i32 s40, s36, 3
	s_lshl_b32 s8, s36, 20
	v_lshl_or_b32 v164, s37, 8, v181
	s_ashr_i32 s41, s40, 31
	v_and_b32_e32 v252, 63, v168
	v_lshlrev_b32_e32 v252, 3, v252
	v_lshrrev_b32_e32 v165, 6, v168
	v_lshl_or_b32 v252, v165, 10, v252
	v_mov_b32_e32 v165, v252
	s_and_b32 s8, s36, 7
	s_lshl_b32 s8, s8, 4
	s_add_i32 s8, s8, s37
	s_lshl_b32 s8, s8, 16
	s_mul_i32 s9, s40, 0x2800000
	s_add_u32 s8, s8, s9
	s_add_u32 s8, s8, 0x9a00000
	s_add_u32 s8, s30, s8
	s_addc_u32 s9, s31, 0
	s_add_u32 s100, s8, 0x80000
	s_addc_u32 s101, s9, 0
	v_mov_b32_e32 v18, v16
	v_mov_b32_e32 v19, v16
	s_add_u32 s37, s42, 0x100
	v_mov_b32_e32 v17, v16
	v_mov_b64_e32 v[22:23], v[18:19]
	v_mov_b64_e32 v[26:27], v[18:19]
	v_mov_b64_e32 v[38:39], v[18:19]
	v_mov_b64_e32 v[42:43], v[18:19]
	v_mov_b64_e32 v[54:55], v[18:19]
	v_mov_b64_e32 v[58:59], v[18:19]
	v_mov_b64_e32 v[70:71], v[18:19]
	v_mov_b64_e32 v[74:75], v[18:19]
	v_mov_b64_e32 v[30:31], v[18:19]
	v_mov_b64_e32 v[34:35], v[18:19]
	v_mov_b64_e32 v[46:47], v[18:19]
	v_mov_b64_e32 v[50:51], v[18:19]
	v_mov_b64_e32 v[62:63], v[18:19]
	v_mov_b64_e32 v[66:67], v[18:19]
	v_mov_b64_e32 v[78:79], v[18:19]
	v_mov_b64_e32 v[82:83], v[18:19]
	v_mov_b64_e32 v[86:87], v[18:19]
	v_mov_b64_e32 v[90:91], v[18:19]
	v_mov_b64_e32 v[102:103], v[18:19]
	v_mov_b64_e32 v[106:107], v[18:19]
	v_mov_b64_e32 v[118:119], v[18:19]
	v_mov_b64_e32 v[122:123], v[18:19]
	v_mov_b64_e32 v[134:135], v[18:19]
	v_mov_b64_e32 v[138:139], v[18:19]
	v_mov_b64_e32 v[94:95], v[18:19]
	v_mov_b64_e32 v[98:99], v[18:19]
	v_mov_b64_e32 v[110:111], v[18:19]
	v_mov_b64_e32 v[114:115], v[18:19]
	v_mov_b64_e32 v[126:127], v[18:19]
	v_mov_b64_e32 v[130:131], v[18:19]
	v_mov_b64_e32 v[142:143], v[18:19]
	v_mov_b64_e32 v[146:147], v[18:19]
	v_add_u32_e32 v183, 0x2000, v165
	v_add_u32_e32 v184, 0x4000, v165
	v_add_u32_e32 v185, 0x6000, v165
	v_add_u32_e32 v186, 0x8000, v165
	v_add_u32_e32 v187, 0xa000, v165
	v_add_u32_e32 v188, 0xc000, v165
	v_add_u32_e32 v189, 0xe000, v165
	v_lshl_add_u64 v[166:167], s[38:39], 0, v[156:157]
	v_lshl_add_u64 v[170:171], s[38:39], 0, v[158:159]
	s_addc_u32 s41, s43, 0
	s_mov_b32 s73, -2
	s_mov_b64 s[42:43], 0
	v_mov_b64_e32 v[20:21], v[16:17]
	v_mov_b64_e32 v[24:25], v[16:17]
	v_mov_b64_e32 v[36:37], v[16:17]
	v_mov_b64_e32 v[40:41], v[16:17]
	v_mov_b64_e32 v[52:53], v[16:17]
	v_mov_b64_e32 v[56:57], v[16:17]
	v_mov_b64_e32 v[68:69], v[16:17]
	v_mov_b64_e32 v[72:73], v[16:17]
	v_mov_b64_e32 v[28:29], v[16:17]
	v_mov_b64_e32 v[32:33], v[16:17]
	v_mov_b64_e32 v[44:45], v[16:17]
	v_mov_b64_e32 v[48:49], v[16:17]
	v_mov_b64_e32 v[60:61], v[16:17]
	v_mov_b64_e32 v[64:65], v[16:17]
	v_mov_b64_e32 v[76:77], v[16:17]
	v_mov_b64_e32 v[80:81], v[16:17]
	v_mov_b64_e32 v[84:85], v[16:17]
	v_mov_b64_e32 v[88:89], v[16:17]
	v_mov_b64_e32 v[100:101], v[16:17]
	v_mov_b64_e32 v[104:105], v[16:17]
	v_mov_b64_e32 v[116:117], v[16:17]
	v_mov_b64_e32 v[120:121], v[16:17]
	v_mov_b64_e32 v[132:133], v[16:17]
	v_mov_b64_e32 v[136:137], v[16:17]
	v_mov_b64_e32 v[92:93], v[16:17]
	v_mov_b64_e32 v[96:97], v[16:17]
	v_mov_b64_e32 v[108:109], v[16:17]
	v_mov_b64_e32 v[112:113], v[16:17]
	v_mov_b64_e32 v[124:125], v[16:17]
	v_mov_b64_e32 v[128:129], v[16:17]
	v_mov_b64_e32 v[140:141], v[16:17]
	v_mov_b64_e32 v[144:145], v[16:17]
	s_branch .LBB0_344

.LBB0_344:
	s_cmpk_lg_i32 s42, 0x200
	s_cbranch_scc1 .LBB0_343
	v_mov_b32_e32 v0, v165
	global_load_dwordx2 v[174:175], v0, s[100:101]
	global_load_dwordx2 v[176:177], v0, s[8:9]
	global_load_dwordx2 v[190:191], v0, s[100:101] offset:512
	global_load_dwordx2 v[192:193], v0, s[8:9] offset:512
	v_mov_b32_e32 v0, v183
	global_load_dwordx2 v[194:195], v0, s[8:9]
	global_load_dwordx2 v[196:197], v0, s[100:101]
	global_load_dwordx2 v[172:173], v0, s[100:101] offset:512
	global_load_dwordx2 v[18:19], v0, s[8:9] offset:512
	v_mov_b32_e32 v1, v184
	global_load_dwordx2 v[12:13], v1, s[8:9]
	global_load_dwordx2 v[14:15], v1, s[100:101]
	global_load_dwordx2 v[10:11], v1, s[100:101] offset:512
	global_load_dwordx2 v[8:9], v1, s[8:9] offset:512
	v_mov_b32_e32 v17, v185
	global_load_dwordx2 v[4:5], v17, s[8:9]
	global_load_dwordx2 v[6:7], v17, s[100:101]
	global_load_dwordx2 v[2:3], v17, s[100:101] offset:512
	global_load_dwordx2 v[0:1], v17, s[8:9] offset:512
	s_waitcnt vmcnt(0)
	v_cvt_f32_ubyte2_e32 v210, v175
	v_cvt_f32_ubyte3_e32 v212, v175
	v_cvt_f32_ubyte0_e32 v17, v174
	v_cvt_f32_ubyte1_e32 v208, v175
	v_cvt_f32_ubyte0_e32 v213, v190
	v_cvt_f32_ubyte1_e32 v215, v190
	v_cvt_f32_ubyte2_e32 v217, v190
	v_cvt_f32_ubyte3_e32 v190, v190
	v_max_f32_e32 v221, 1.0, v210
	v_max_f32_e32 v222, 1.0, v212
	v_cvt_f32_ubyte0_e32 v206, v175
	v_cvt_f32_ubyte2_e32 v209, v174
	v_cvt_f32_ubyte2_e32 v218, v191
	v_max_f32_e32 v17, 1.0, v17
	v_max_f32_e32 v219, 1.0, v208
	v_max_f32_e32 v223, 1.0, v213
	v_max_f32_e32 v226, 1.0, v217
	v_max_f32_e32 v228, 1.0, v190
	v_rcp_f32_e32 v212, v221
	v_rcp_f32_e32 v213, v222
	v_cvt_f32_ubyte1_e32 v207, v174
	v_cvt_f32_ubyte3_e32 v211, v174
	v_cvt_f32_ubyte3_e32 v199, v176
	v_cvt_f32_ubyte2_e32 v198, v176
	v_cvt_f32_ubyte1_e32 v201, v176
	v_cvt_f32_ubyte0_e32 v200, v176
	v_cvt_f32_ubyte3_e32 v175, v177
	v_cvt_f32_ubyte2_e32 v174, v177
	v_cvt_f32_ubyte1_e32 v203, v177
	v_cvt_f32_ubyte0_e32 v202, v177
	v_cvt_f32_ubyte3_e32 v177, v192
	v_cvt_f32_ubyte2_e32 v176, v192
	v_cvt_f32_ubyte1_e32 v205, v192
	v_cvt_f32_ubyte0_e32 v204, v192
	v_max_f32_e32 v192, 1.0, v206
	v_max_f32_e32 v220, 1.0, v209
	v_max_f32_e32 v227, 1.0, v218
	v_rcp_f32_e32 v206, v17
	v_rcp_f32_e32 v209, v219
	v_rcp_f32_e32 v218, v226
	v_rcp_f32_e32 v219, v228
	v_cvt_f32_ubyte3_e32 v17, v191
	v_max_f32_e32 v17, 1.0, v17
	v_cvt_f32_ubyte0_e32 v214, v191
	v_cvt_f32_ubyte1_e32 v216, v191
	v_rcp_f32_e32 v190, v227
	v_rcp_f32_e32 v191, v17
	v_max_f32_e32 v224, 1.0, v214
	v_max_f32_e32 v225, 1.0, v216
	v_pk_mul_f32 v[174:175], v[212:213], v[174:175]
	v_rcp_f32_e32 v216, v224
	v_rcp_f32_e32 v217, v225
	v_pk_mul_f32 v[142:143], v[142:143], v[174:175]
	v_pk_mul_f32 v[174:175], v[218:219], v[176:177]
	v_cvt_f32_ubyte0_e32 v17, v196
	v_pk_mul_f32 v[138:139], v[138:139], v[174:175]
	v_cvt_f32_ubyte3_e32 v175, v193
	v_cvt_f32_ubyte2_e32 v174, v193
	v_pk_mul_f32 v[174:175], v[190:191], v[174:175]
	v_max_f32_e32 v17, 1.0, v17
	v_cvt_f32_ubyte1_e32 v177, v193
	v_cvt_f32_ubyte0_e32 v176, v193
	v_pk_mul_f32 v[134:135], v[134:135], v[174:175]
	v_rcp_f32_e32 v174, v17
	v_cvt_f32_ubyte0_e32 v17, v197
	v_pk_mul_f32 v[176:177], v[216:217], v[176:177]
	v_max_f32_e32 v17, 1.0, v17
	v_pk_mul_f32 v[132:133], v[132:133], v[176:177]
	v_rcp_f32_e32 v176, v17
	v_cvt_f32_ubyte1_e32 v17, v196
	v_max_f32_e32 v17, 1.0, v17
	v_rcp_f32_e32 v175, v17
	v_cvt_f32_ubyte1_e32 v17, v197
	v_max_f32_e32 v17, 1.0, v17
	v_rcp_f32_e32 v177, v17
	v_cvt_f32_ubyte2_e32 v17, v196
	v_max_f32_e32 v17, 1.0, v17
	v_rcp_f32_e32 v190, v17
	v_cvt_f32_ubyte2_e32 v17, v197
	v_max_f32_e32 v207, 1.0, v207
	v_max_f32_e32 v17, 1.0, v17
	v_rcp_f32_e32 v208, v192
	v_rcp_f32_e32 v207, v207
	v_rcp_f32_e32 v192, v17
	v_cvt_f32_ubyte3_e32 v17, v196
	v_max_f32_e32 v211, 1.0, v211
	v_max_f32_e32 v17, 1.0, v17
	v_rcp_f32_e32 v210, v220
	v_rcp_f32_e32 v211, v211
	v_rcp_f32_e32 v191, v17
	v_cvt_f32_ubyte3_e32 v17, v197
	v_max_f32_e32 v17, 1.0, v17
	v_pk_mul_f32 v[200:201], v[206:207], v[200:201]
	v_rcp_f32_e32 v193, v17
	v_pk_mul_f32 v[144:145], v[144:145], v[200:201]
	v_cvt_f32_ubyte1_e32 v201, v194
	v_cvt_f32_ubyte0_e32 v200, v194
	v_pk_mul_f32 v[198:199], v[210:211], v[198:199]
	v_pk_mul_f32 v[174:175], v[174:175], v[200:201]
	v_pk_mul_f32 v[146:147], v[146:147], v[198:199]
	v_cvt_f32_ubyte3_e32 v199, v194
	v_cvt_f32_ubyte2_e32 v198, v194
	v_pk_mul_f32 v[128:129], v[128:129], v[174:175]
	v_cvt_f32_ubyte3_e32 v175, v195
	v_cvt_f32_ubyte2_e32 v174, v195
	v_cvt_f32_ubyte0_e32 v17, v172
	v_pk_mul_f32 v[190:191], v[190:191], v[198:199]
	v_pk_mul_f32 v[174:175], v[192:193], v[174:175]
	v_max_f32_e32 v17, 1.0, v17
	v_pk_mul_f32 v[130:131], v[130:131], v[190:191]
	v_cvt_f32_ubyte1_e32 v191, v195
	v_cvt_f32_ubyte0_e32 v190, v195
	v_pk_mul_f32 v[126:127], v[126:127], v[174:175]
	v_rcp_f32_e32 v174, v17
	v_cvt_f32_ubyte0_e32 v17, v173
	v_pk_mul_f32 v[176:177], v[176:177], v[190:191]
	v_max_f32_e32 v17, 1.0, v17
	v_pk_mul_f32 v[124:125], v[124:125], v[176:177]
	v_rcp_f32_e32 v176, v17
	v_cvt_f32_ubyte1_e32 v17, v172
	v_max_f32_e32 v17, 1.0, v17
	v_rcp_f32_e32 v175, v17
	v_cvt_f32_ubyte1_e32 v17, v173
	v_max_f32_e32 v17, 1.0, v17
	v_rcp_f32_e32 v177, v17
	v_cvt_f32_ubyte2_e32 v17, v172
	v_max_f32_e32 v17, 1.0, v17
	v_rcp_f32_e32 v190, v17
	v_cvt_f32_ubyte2_e32 v17, v173
	v_max_f32_e32 v17, 1.0, v17
	v_rcp_f32_e32 v192, v17
	v_cvt_f32_ubyte3_e32 v17, v172
	v_max_f32_e32 v17, 1.0, v17
	v_rcp_f32_e32 v191, v17
	v_cvt_f32_ubyte3_e32 v17, v173
	v_cvt_f32_ubyte1_e32 v197, v18
	v_cvt_f32_ubyte0_e32 v196, v18
	v_max_f32_e32 v17, 1.0, v17
	v_pk_mul_f32 v[174:175], v[174:175], v[196:197]
	v_rcp_f32_e32 v193, v17
	v_pk_mul_f32 v[120:121], v[120:121], v[174:175]
	v_cvt_f32_ubyte1_e32 v175, v19
	v_cvt_f32_ubyte0_e32 v174, v19
	v_cvt_f32_ubyte0_e32 v17, v14
	v_cvt_f32_ubyte3_e32 v195, v18
	v_cvt_f32_ubyte2_e32 v194, v18
	v_cvt_f32_ubyte3_e32 v173, v19
	v_cvt_f32_ubyte2_e32 v172, v19
	v_pk_mul_f32 v[18:19], v[176:177], v[174:175]
	v_max_f32_e32 v17, 1.0, v17
	v_pk_mul_f32 v[116:117], v[116:117], v[18:19]
	v_rcp_f32_e32 v18, v17
	v_cvt_f32_ubyte0_e32 v17, v15
	v_pk_mul_f32 v[172:173], v[192:193], v[172:173]
	v_max_f32_e32 v17, 1.0, v17
	v_pk_mul_f32 v[118:119], v[118:119], v[172:173]
	v_rcp_f32_e32 v172, v17
	v_cvt_f32_ubyte1_e32 v17, v14
	v_max_f32_e32 v17, 1.0, v17
	v_rcp_f32_e32 v19, v17
	v_cvt_f32_ubyte1_e32 v17, v15
	v_max_f32_e32 v17, 1.0, v17
	v_rcp_f32_e32 v173, v17
	v_cvt_f32_ubyte2_e32 v17, v14
	v_pk_mul_f32 v[190:191], v[190:191], v[194:195]
	v_max_f32_e32 v17, 1.0, v17
	v_pk_mul_f32 v[122:123], v[122:123], v[190:191]
	v_rcp_f32_e32 v174, v17
	v_cvt_f32_ubyte2_e32 v17, v15
	v_cvt_f32_ubyte3_e32 v191, v12
	v_cvt_f32_ubyte2_e32 v190, v12
	v_cvt_f32_ubyte1_e32 v193, v12
	v_cvt_f32_ubyte0_e32 v192, v12
	v_cvt_f32_ubyte3_e32 v12, v15
	v_max_f32_e32 v17, 1.0, v17
	v_max_f32_e32 v12, 1.0, v12
	v_rcp_f32_e32 v176, v17
	v_cvt_f32_ubyte3_e32 v14, v14
	v_pk_mul_f32 v[18:19], v[18:19], v[192:193]
	v_rcp_f32_e32 v177, v12
	v_max_f32_e32 v14, 1.0, v14
	v_pk_mul_f32 v[112:113], v[112:113], v[18:19]
	v_cvt_f32_ubyte1_e32 v19, v13
	v_cvt_f32_ubyte0_e32 v18, v13
	v_rcp_f32_e32 v175, v14
	v_cvt_f32_ubyte3_e32 v15, v13
	v_cvt_f32_ubyte2_e32 v14, v13
	v_pk_mul_f32 v[12:13], v[172:173], v[18:19]
	v_pk_mul_f32 v[14:15], v[176:177], v[14:15]
	v_pk_mul_f32 v[108:109], v[108:109], v[12:13]
	v_cvt_f32_ubyte0_e32 v13, v11
	v_max_f32_e32 v13, 1.0, v13
	v_pk_mul_f32 v[110:111], v[110:111], v[14:15]
	v_cvt_f32_ubyte0_e32 v12, v10
	v_rcp_f32_e32 v14, v13
	v_cvt_f32_ubyte1_e32 v13, v10
	v_cvt_f32_ubyte2_e32 v17, v10
	v_cvt_f32_ubyte3_e32 v10, v10
	v_max_f32_e32 v17, 1.0, v17
	v_max_f32_e32 v10, 1.0, v10
	v_rcp_f32_e32 v18, v17
	v_rcp_f32_e32 v19, v10
	v_cvt_f32_ubyte2_e32 v17, v11
	v_pk_mul_f32 v[174:175], v[174:175], v[190:191]
	v_max_f32_e32 v17, 1.0, v17
	v_pk_mul_f32 v[114:115], v[114:115], v[174:175]
	v_rcp_f32_e32 v172, v17
	v_cvt_f32_ubyte3_e32 v175, v8
	v_cvt_f32_ubyte2_e32 v174, v8
	v_mov_b32_e32 v17, v186
	v_pk_mul_f32 v[18:19], v[18:19], v[174:175]
	global_load_dwordx2 v[174:175], v17, s[100:101]
	global_load_dwordx2 v[190:191], v17, s[100:101] offset:512
	global_load_dwordx2 v[192:193], v17, s[8:9] offset:512
	v_max_f32_e32 v12, 1.0, v12
	v_max_f32_e32 v13, 1.0, v13
	v_rcp_f32_e32 v12, v12
	v_rcp_f32_e32 v13, v13
	v_cvt_f32_ubyte1_e32 v15, v11
	v_max_f32_e32 v15, 1.0, v15
	v_rcp_f32_e32 v15, v15
	v_cvt_f32_ubyte1_e32 v177, v8
	v_cvt_f32_ubyte0_e32 v176, v8
	v_cvt_f32_ubyte3_e32 v8, v11
	v_max_f32_e32 v8, 1.0, v8
	v_pk_mul_f32 v[12:13], v[12:13], v[176:177]
	v_rcp_f32_e32 v173, v8
	v_pk_mul_f32 v[104:105], v[104:105], v[12:13]
	v_cvt_f32_ubyte1_e32 v13, v9
	v_cvt_f32_ubyte0_e32 v12, v9
	v_cvt_f32_ubyte3_e32 v11, v9
	v_cvt_f32_ubyte2_e32 v10, v9
	v_pk_mul_f32 v[8:9], v[14:15], v[12:13]
	v_pk_mul_f32 v[10:11], v[172:173], v[10:11]
	v_pk_mul_f32 v[100:101], v[100:101], v[8:9]
	v_cvt_f32_ubyte0_e32 v9, v7
	v_max_f32_e32 v9, 1.0, v9
	v_pk_mul_f32 v[102:103], v[102:103], v[10:11]
	v_cvt_f32_ubyte0_e32 v8, v6
	v_rcp_f32_e32 v10, v9
	v_cvt_f32_ubyte1_e32 v9, v6
	v_max_f32_e32 v8, 1.0, v8
	v_max_f32_e32 v9, 1.0, v9
	global_load_dwordx2 v[176:177], v17, s[8:9]
	v_rcp_f32_e32 v8, v8
	v_rcp_f32_e32 v9, v9
	v_cvt_f32_ubyte1_e32 v11, v7
	v_max_f32_e32 v11, 1.0, v11
	v_pk_mul_f32 v[106:107], v[106:107], v[18:19]
	v_rcp_f32_e32 v11, v11
	v_cvt_f32_ubyte2_e32 v13, v7
	v_cvt_f32_ubyte3_e32 v19, v4
	v_cvt_f32_ubyte2_e32 v18, v4
	v_cvt_f32_ubyte1_e32 v173, v4
	v_cvt_f32_ubyte0_e32 v172, v4
	v_cvt_f32_ubyte3_e32 v4, v7
	v_max_f32_e32 v13, 1.0, v13
	v_max_f32_e32 v4, 1.0, v4
	v_cvt_f32_ubyte2_e32 v12, v6
	v_rcp_f32_e32 v14, v13
	v_cvt_f32_ubyte3_e32 v6, v6
	v_pk_mul_f32 v[8:9], v[8:9], v[172:173]
	v_rcp_f32_e32 v15, v4
	v_max_f32_e32 v6, 1.0, v6
	v_pk_mul_f32 v[96:97], v[96:97], v[8:9]
	v_cvt_f32_ubyte1_e32 v9, v5
	v_cvt_f32_ubyte0_e32 v8, v5
	v_rcp_f32_e32 v13, v6
	v_cvt_f32_ubyte3_e32 v7, v5
	v_cvt_f32_ubyte2_e32 v6, v5
	v_pk_mul_f32 v[4:5], v[10:11], v[8:9]
	v_pk_mul_f32 v[6:7], v[14:15], v[6:7]
	v_pk_mul_f32 v[92:93], v[92:93], v[4:5]
	v_cvt_f32_ubyte0_e32 v5, v3
	v_max_f32_e32 v5, 1.0, v5
	v_max_f32_e32 v12, 1.0, v12
	v_pk_mul_f32 v[94:95], v[94:95], v[6:7]
	v_cvt_f32_ubyte0_e32 v4, v2
	v_rcp_f32_e32 v6, v5
	v_cvt_f32_ubyte1_e32 v5, v2
	v_rcp_f32_e32 v12, v12
	v_max_f32_e32 v4, 1.0, v4
	v_max_f32_e32 v5, 1.0, v5
	v_rcp_f32_e32 v4, v4
	v_rcp_f32_e32 v5, v5
	v_cvt_f32_ubyte1_e32 v7, v3
	v_max_f32_e32 v7, 1.0, v7
	v_rcp_f32_e32 v7, v7
	v_pk_mul_f32 v[12:13], v[12:13], v[18:19]
	v_cvt_f32_ubyte1_e32 v15, v0
	v_cvt_f32_ubyte0_e32 v14, v0
	v_pk_mul_f32 v[98:99], v[98:99], v[12:13]
	v_cvt_f32_ubyte2_e32 v8, v2
	v_cvt_f32_ubyte2_e32 v9, v3
	v_cvt_f32_ubyte3_e32 v2, v2
	v_cvt_f32_ubyte3_e32 v13, v0
	v_cvt_f32_ubyte2_e32 v12, v0
	v_pk_mul_f32 v[4:5], v[4:5], v[14:15]
	v_cvt_f32_ubyte3_e32 v0, v3
	v_max_f32_e32 v9, 1.0, v9
	v_max_f32_e32 v2, 1.0, v2
	v_pk_mul_f32 v[88:89], v[88:89], v[4:5]
	v_max_f32_e32 v0, 1.0, v0
	v_cvt_f32_ubyte1_e32 v5, v1
	v_cvt_f32_ubyte0_e32 v4, v1
	v_rcp_f32_e32 v10, v9
	v_rcp_f32_e32 v9, v2
	v_rcp_f32_e32 v11, v0
	v_cvt_f32_ubyte3_e32 v3, v1
	v_cvt_f32_ubyte2_e32 v2, v1
	v_pk_mul_f32 v[0:1], v[6:7], v[4:5]
	v_max_f32_e32 v8, 1.0, v8
	v_pk_mul_f32 v[84:85], v[84:85], v[0:1]
	v_mov_b32_e32 v0, v187
	global_load_dwordx2 v[194:195], v0, s[8:9]
	global_load_dwordx2 v[196:197], v0, s[100:101]
	global_load_dwordx2 v[172:173], v0, s[100:101] offset:512
	global_load_dwordx2 v[18:19], v0, s[8:9] offset:512
	v_rcp_f32_e32 v8, v8
	v_mov_b32_e32 v0, v188
	v_pk_mul_f32 v[2:3], v[10:11], v[2:3]
	v_pk_mul_f32 v[8:9], v[8:9], v[12:13]
	s_waitcnt vmcnt(0)
	v_cvt_f32_ubyte0_e32 v17, v174
	v_pk_mul_f32 v[90:91], v[90:91], v[8:9]
	global_load_dwordx2 v[12:13], v0, s[8:9]
	global_load_dwordx2 v[14:15], v0, s[100:101]
	global_load_dwordx2 v[10:11], v0, s[100:101] offset:512
	global_load_dwordx2 v[8:9], v0, s[8:9] offset:512
	v_max_f32_e32 v17, 1.0, v17
	v_rcp_f32_e32 v198, v17
	v_cvt_f32_ubyte0_e32 v17, v175
	v_max_f32_e32 v17, 1.0, v17
	v_rcp_f32_e32 v200, v17
	v_cvt_f32_ubyte1_e32 v17, v174
	v_max_f32_e32 v17, 1.0, v17
	v_max_f32_e32 v215, 1.0, v215
	v_rcp_f32_e32 v199, v17
	v_cvt_f32_ubyte1_e32 v17, v175
	v_rcp_f32_e32 v214, v223
	v_rcp_f32_e32 v215, v215
	v_max_f32_e32 v17, 1.0, v17
	v_rcp_f32_e32 v201, v17
	v_cvt_f32_ubyte2_e32 v17, v174
	v_pk_mul_f32 v[202:203], v[208:209], v[202:203]
	v_max_f32_e32 v17, 1.0, v17
	v_pk_mul_f32 v[140:141], v[140:141], v[202:203]
	v_rcp_f32_e32 v202, v17
	v_cvt_f32_ubyte2_e32 v17, v175
	v_pk_mul_f32 v[204:205], v[214:215], v[204:205]
	v_max_f32_e32 v17, 1.0, v17
	v_pk_mul_f32 v[136:137], v[136:137], v[204:205]
	v_rcp_f32_e32 v204, v17
	v_cvt_f32_ubyte3_e32 v17, v174
	v_max_f32_e32 v17, 1.0, v17
	v_rcp_f32_e32 v203, v17
	v_cvt_f32_ubyte3_e32 v17, v175
	v_max_f32_e32 v17, 1.0, v17
	v_rcp_f32_e32 v205, v17
	v_cvt_f32_ubyte1_e32 v209, v176
	v_cvt_f32_ubyte0_e32 v208, v176
	v_cvt_f32_ubyte3_e32 v175, v177
	v_cvt_f32_ubyte2_e32 v174, v177
	v_cvt_f32_ubyte0_e32 v17, v190
	v_mov_b32_e32 v0, v189
	v_pk_mul_f32 v[198:199], v[198:199], v[208:209]
	v_pk_mul_f32 v[174:175], v[204:205], v[174:175]
	v_max_f32_e32 v17, 1.0, v17
	v_pk_mul_f32 v[80:81], v[80:81], v[198:199]
	v_cvt_f32_ubyte1_e32 v199, v177
	v_cvt_f32_ubyte0_e32 v198, v177
	v_pk_mul_f32 v[78:79], v[78:79], v[174:175]
	v_rcp_f32_e32 v174, v17
	v_cvt_f32_ubyte0_e32 v17, v191
	v_pk_mul_f32 v[86:87], v[86:87], v[2:3]
	global_load_dwordx2 v[4:5], v0, s[8:9]
	global_load_dwordx2 v[6:7], v0, s[100:101]
	global_load_dwordx2 v[2:3], v0, s[100:101] offset:512
	s_nop 0
	global_load_dwordx2 v[0:1], v0, s[8:9] offset:512
	v_cvt_f32_ubyte3_e32 v207, v176
	v_cvt_f32_ubyte2_e32 v206, v176
	v_pk_mul_f32 v[176:177], v[200:201], v[198:199]
	v_max_f32_e32 v17, 1.0, v17
	v_pk_mul_f32 v[76:77], v[76:77], v[176:177]
	v_rcp_f32_e32 v176, v17
	v_cvt_f32_ubyte1_e32 v17, v190
	v_max_f32_e32 v17, 1.0, v17
	v_rcp_f32_e32 v175, v17
	v_cvt_f32_ubyte1_e32 v17, v191
	v_max_f32_e32 v17, 1.0, v17
	v_rcp_f32_e32 v177, v17
	v_cvt_f32_ubyte2_e32 v17, v190
	v_max_f32_e32 v17, 1.0, v17
	v_rcp_f32_e32 v198, v17
	v_cvt_f32_ubyte2_e32 v17, v191
	v_max_f32_e32 v17, 1.0, v17
	v_rcp_f32_e32 v200, v17
	v_cvt_f32_ubyte3_e32 v17, v190
	v_max_f32_e32 v17, 1.0, v17
	v_rcp_f32_e32 v199, v17
	v_cvt_f32_ubyte3_e32 v17, v191
	v_max_f32_e32 v17, 1.0, v17
	v_rcp_f32_e32 v201, v17
	v_cvt_f32_ubyte1_e32 v205, v192
	v_cvt_f32_ubyte0_e32 v204, v192
	v_pk_mul_f32 v[174:175], v[174:175], v[204:205]
	v_cvt_f32_ubyte0_e32 v17, v196
	v_pk_mul_f32 v[72:73], v[72:73], v[174:175]
	v_cvt_f32_ubyte3_e32 v175, v193
	v_cvt_f32_ubyte2_e32 v174, v193
	v_pk_mul_f32 v[174:175], v[200:201], v[174:175]
	v_max_f32_e32 v17, 1.0, v17
	v_cvt_f32_ubyte1_e32 v191, v193
	v_cvt_f32_ubyte0_e32 v190, v193
	v_pk_mul_f32 v[70:71], v[70:71], v[174:175]
	v_rcp_f32_e32 v174, v17
	v_cvt_f32_ubyte0_e32 v17, v197
	v_pk_mul_f32 v[176:177], v[176:177], v[190:191]
	v_max_f32_e32 v17, 1.0, v17
	v_pk_mul_f32 v[68:69], v[68:69], v[176:177]
	v_rcp_f32_e32 v176, v17
	v_cvt_f32_ubyte1_e32 v17, v196
	v_max_f32_e32 v17, 1.0, v17
	v_rcp_f32_e32 v175, v17
	v_cvt_f32_ubyte1_e32 v17, v197
	v_max_f32_e32 v17, 1.0, v17
	v_rcp_f32_e32 v177, v17
	v_cvt_f32_ubyte2_e32 v17, v196
	v_max_f32_e32 v17, 1.0, v17
	v_rcp_f32_e32 v190, v17
	v_cvt_f32_ubyte2_e32 v17, v197
	v_pk_mul_f32 v[202:203], v[202:203], v[206:207]
	v_max_f32_e32 v17, 1.0, v17
	v_pk_mul_f32 v[82:83], v[82:83], v[202:203]
	v_cvt_f32_ubyte3_e32 v203, v192
	v_cvt_f32_ubyte2_e32 v202, v192
	v_rcp_f32_e32 v192, v17
	v_cvt_f32_ubyte3_e32 v17, v196
	v_max_f32_e32 v17, 1.0, v17
	v_rcp_f32_e32 v191, v17
	v_cvt_f32_ubyte3_e32 v17, v197
	v_max_f32_e32 v17, 1.0, v17
	v_rcp_f32_e32 v193, v17
	v_cvt_f32_ubyte1_e32 v201, v194
	v_cvt_f32_ubyte0_e32 v200, v194
	v_pk_mul_f32 v[198:199], v[198:199], v[202:203]
	v_pk_mul_f32 v[174:175], v[174:175], v[200:201]
	v_pk_mul_f32 v[74:75], v[74:75], v[198:199]
	v_cvt_f32_ubyte3_e32 v199, v194
	v_cvt_f32_ubyte2_e32 v198, v194
	v_pk_mul_f32 v[64:65], v[64:65], v[174:175]
	v_cvt_f32_ubyte3_e32 v175, v195
	v_cvt_f32_ubyte2_e32 v174, v195
	v_cvt_f32_ubyte0_e32 v17, v172
	v_pk_mul_f32 v[190:191], v[190:191], v[198:199]
	v_pk_mul_f32 v[174:175], v[192:193], v[174:175]
	v_max_f32_e32 v17, 1.0, v17
	v_pk_mul_f32 v[66:67], v[66:67], v[190:191]
	v_cvt_f32_ubyte1_e32 v191, v195
	v_cvt_f32_ubyte0_e32 v190, v195
	v_pk_mul_f32 v[62:63], v[62:63], v[174:175]
	v_rcp_f32_e32 v174, v17
	v_cvt_f32_ubyte0_e32 v17, v173
	v_pk_mul_f32 v[176:177], v[176:177], v[190:191]
	v_max_f32_e32 v17, 1.0, v17
	v_pk_mul_f32 v[60:61], v[60:61], v[176:177]
	v_rcp_f32_e32 v176, v17
	v_cvt_f32_ubyte1_e32 v17, v172
	v_max_f32_e32 v17, 1.0, v17
	v_rcp_f32_e32 v175, v17
	v_cvt_f32_ubyte1_e32 v17, v173
	v_max_f32_e32 v17, 1.0, v17
	v_rcp_f32_e32 v177, v17
	v_cvt_f32_ubyte2_e32 v17, v172
	v_max_f32_e32 v17, 1.0, v17
	v_rcp_f32_e32 v190, v17
	v_cvt_f32_ubyte2_e32 v17, v173
	v_max_f32_e32 v17, 1.0, v17
	v_rcp_f32_e32 v192, v17
	v_cvt_f32_ubyte3_e32 v17, v172
	v_max_f32_e32 v17, 1.0, v17
	v_rcp_f32_e32 v191, v17
	v_cvt_f32_ubyte3_e32 v17, v173
	v_cvt_f32_ubyte1_e32 v197, v18
	v_cvt_f32_ubyte0_e32 v196, v18
	v_max_f32_e32 v17, 1.0, v17
	v_pk_mul_f32 v[174:175], v[174:175], v[196:197]
	v_rcp_f32_e32 v193, v17
	v_pk_mul_f32 v[56:57], v[56:57], v[174:175]
	v_cvt_f32_ubyte1_e32 v175, v19
	v_cvt_f32_ubyte0_e32 v174, v19
	s_waitcnt vmcnt(0)
	v_cvt_f32_ubyte0_e32 v17, v14
	v_cvt_f32_ubyte3_e32 v195, v18
	v_cvt_f32_ubyte2_e32 v194, v18
	v_cvt_f32_ubyte3_e32 v173, v19
	v_cvt_f32_ubyte2_e32 v172, v19
	v_pk_mul_f32 v[18:19], v[176:177], v[174:175]
	v_max_f32_e32 v17, 1.0, v17
	v_pk_mul_f32 v[52:53], v[52:53], v[18:19]
	v_rcp_f32_e32 v18, v17
	v_cvt_f32_ubyte0_e32 v17, v15
	v_pk_mul_f32 v[172:173], v[192:193], v[172:173]
	v_max_f32_e32 v17, 1.0, v17
	v_pk_mul_f32 v[54:55], v[54:55], v[172:173]
	v_rcp_f32_e32 v172, v17
	v_cvt_f32_ubyte1_e32 v17, v14
	v_max_f32_e32 v17, 1.0, v17
	v_rcp_f32_e32 v19, v17
	v_cvt_f32_ubyte1_e32 v17, v15
	v_max_f32_e32 v17, 1.0, v17
	v_rcp_f32_e32 v173, v17
	v_cvt_f32_ubyte2_e32 v17, v14
	v_pk_mul_f32 v[190:191], v[190:191], v[194:195]
	v_max_f32_e32 v17, 1.0, v17
	v_pk_mul_f32 v[58:59], v[58:59], v[190:191]
	v_rcp_f32_e32 v174, v17
	v_cvt_f32_ubyte2_e32 v17, v15
	v_cvt_f32_ubyte3_e32 v191, v12
	v_cvt_f32_ubyte2_e32 v190, v12
	v_cvt_f32_ubyte1_e32 v193, v12
	v_cvt_f32_ubyte0_e32 v192, v12
	v_cvt_f32_ubyte3_e32 v12, v15
	v_max_f32_e32 v17, 1.0, v17
	v_max_f32_e32 v12, 1.0, v12
	v_rcp_f32_e32 v176, v17
	v_cvt_f32_ubyte3_e32 v14, v14
	v_pk_mul_f32 v[18:19], v[18:19], v[192:193]
	v_rcp_f32_e32 v177, v12
	v_max_f32_e32 v14, 1.0, v14
	v_pk_mul_f32 v[48:49], v[48:49], v[18:19]
	v_cvt_f32_ubyte1_e32 v19, v13
	v_cvt_f32_ubyte0_e32 v18, v13
	v_rcp_f32_e32 v175, v14
	v_cvt_f32_ubyte3_e32 v15, v13
	v_cvt_f32_ubyte2_e32 v14, v13
	v_pk_mul_f32 v[12:13], v[172:173], v[18:19]
	v_pk_mul_f32 v[14:15], v[176:177], v[14:15]
	v_pk_mul_f32 v[44:45], v[44:45], v[12:13]
	v_cvt_f32_ubyte0_e32 v13, v11
	v_max_f32_e32 v13, 1.0, v13
	v_pk_mul_f32 v[46:47], v[46:47], v[14:15]
	v_cvt_f32_ubyte0_e32 v12, v10
	v_rcp_f32_e32 v14, v13
	v_cvt_f32_ubyte1_e32 v13, v10
	v_max_f32_e32 v12, 1.0, v12
	v_max_f32_e32 v13, 1.0, v13
	v_rcp_f32_e32 v12, v12
	v_rcp_f32_e32 v13, v13
	v_cvt_f32_ubyte1_e32 v15, v11
	v_cvt_f32_ubyte2_e32 v17, v10
	v_pk_mul_f32 v[174:175], v[174:175], v[190:191]
	v_max_f32_e32 v15, 1.0, v15
	v_max_f32_e32 v17, 1.0, v17
	v_pk_mul_f32 v[50:51], v[50:51], v[174:175]
	v_rcp_f32_e32 v15, v15
	v_rcp_f32_e32 v18, v17
	v_cvt_f32_ubyte2_e32 v17, v11
	v_cvt_f32_ubyte3_e32 v175, v8
	v_cvt_f32_ubyte2_e32 v174, v8
	v_cvt_f32_ubyte1_e32 v177, v8
	v_cvt_f32_ubyte0_e32 v176, v8
	v_cvt_f32_ubyte3_e32 v8, v11
	v_max_f32_e32 v17, 1.0, v17
	v_max_f32_e32 v8, 1.0, v8
	v_rcp_f32_e32 v172, v17
	v_cvt_f32_ubyte3_e32 v10, v10
	v_pk_mul_f32 v[12:13], v[12:13], v[176:177]
	v_rcp_f32_e32 v173, v8
	v_max_f32_e32 v10, 1.0, v10
	v_pk_mul_f32 v[40:41], v[40:41], v[12:13]
	v_cvt_f32_ubyte1_e32 v13, v9
	v_cvt_f32_ubyte0_e32 v12, v9
	v_rcp_f32_e32 v19, v10
	v_cvt_f32_ubyte3_e32 v11, v9
	v_cvt_f32_ubyte2_e32 v10, v9
	v_pk_mul_f32 v[8:9], v[14:15], v[12:13]
	v_pk_mul_f32 v[10:11], v[172:173], v[10:11]
	v_pk_mul_f32 v[36:37], v[36:37], v[8:9]
	v_cvt_f32_ubyte0_e32 v9, v7
	v_max_f32_e32 v9, 1.0, v9
	v_pk_mul_f32 v[38:39], v[38:39], v[10:11]
	v_cvt_f32_ubyte0_e32 v8, v6
	v_rcp_f32_e32 v10, v9
	v_cvt_f32_ubyte1_e32 v9, v6
	v_max_f32_e32 v8, 1.0, v8
	v_max_f32_e32 v9, 1.0, v9
	v_rcp_f32_e32 v8, v8
	v_rcp_f32_e32 v9, v9
	v_cvt_f32_ubyte1_e32 v11, v7
	v_pk_mul_f32 v[18:19], v[18:19], v[174:175]
	v_max_f32_e32 v11, 1.0, v11
	v_pk_mul_f32 v[42:43], v[42:43], v[18:19]
	v_rcp_f32_e32 v11, v11
	v_cvt_f32_ubyte2_e32 v13, v7
	v_cvt_f32_ubyte3_e32 v19, v4
	v_cvt_f32_ubyte2_e32 v18, v4
	v_cvt_f32_ubyte1_e32 v173, v4
	v_cvt_f32_ubyte0_e32 v172, v4
	v_cvt_f32_ubyte3_e32 v4, v7
	v_max_f32_e32 v13, 1.0, v13
	v_max_f32_e32 v4, 1.0, v4
	v_cvt_f32_ubyte2_e32 v12, v6
	v_rcp_f32_e32 v14, v13
	v_cvt_f32_ubyte3_e32 v6, v6
	v_pk_mul_f32 v[8:9], v[8:9], v[172:173]
	v_rcp_f32_e32 v15, v4
	v_max_f32_e32 v12, 1.0, v12
	v_max_f32_e32 v6, 1.0, v6
	v_pk_mul_f32 v[32:33], v[32:33], v[8:9]
	v_cvt_f32_ubyte1_e32 v9, v5
	v_cvt_f32_ubyte0_e32 v8, v5
	v_rcp_f32_e32 v12, v12
	v_rcp_f32_e32 v13, v6
	v_cvt_f32_ubyte3_e32 v7, v5
	v_cvt_f32_ubyte2_e32 v6, v5
	v_pk_mul_f32 v[4:5], v[10:11], v[8:9]
	v_pk_mul_f32 v[6:7], v[14:15], v[6:7]
	v_pk_mul_f32 v[28:29], v[28:29], v[4:5]
	v_cvt_f32_ubyte0_e32 v5, v3
	v_max_f32_e32 v5, 1.0, v5
	v_pk_mul_f32 v[30:31], v[30:31], v[6:7]
	v_cvt_f32_ubyte0_e32 v4, v2
	v_rcp_f32_e32 v6, v5
	v_cvt_f32_ubyte1_e32 v5, v2
	v_pk_mul_f32 v[12:13], v[12:13], v[18:19]
	v_max_f32_e32 v4, 1.0, v4
	v_max_f32_e32 v5, 1.0, v5
	v_pk_mul_f32 v[34:35], v[34:35], v[12:13]
	v_rcp_f32_e32 v4, v4
	v_rcp_f32_e32 v5, v5
	v_cvt_f32_ubyte1_e32 v7, v3
	v_cvt_f32_ubyte2_e32 v8, v2
	v_cvt_f32_ubyte2_e32 v9, v3
	v_cvt_f32_ubyte3_e32 v2, v2
	v_cvt_f32_ubyte3_e32 v13, v0
	v_cvt_f32_ubyte2_e32 v12, v0
	v_cvt_f32_ubyte1_e32 v15, v0
	v_cvt_f32_ubyte0_e32 v14, v0
	v_cvt_f32_ubyte3_e32 v0, v3
	v_max_f32_e32 v7, 1.0, v7
	v_max_f32_e32 v8, 1.0, v8
	v_max_f32_e32 v9, 1.0, v9
	v_max_f32_e32 v2, 1.0, v2
	v_max_f32_e32 v0, 1.0, v0
	v_rcp_f32_e32 v7, v7
	v_rcp_f32_e32 v8, v8
	v_rcp_f32_e32 v10, v9
	v_rcp_f32_e32 v9, v2
	v_rcp_f32_e32 v11, v0
	v_pk_mul_f32 v[4:5], v[4:5], v[14:15]
	v_cvt_f32_ubyte3_e32 v3, v1
	v_pk_mul_f32 v[24:25], v[24:25], v[4:5]
	v_cvt_f32_ubyte2_e32 v2, v1
	v_cvt_f32_ubyte1_e32 v5, v1
	v_cvt_f32_ubyte0_e32 v4, v1
	v_pk_mul_f32 v[8:9], v[8:9], v[12:13]
	v_pk_mul_f32 v[0:1], v[6:7], v[4:5]
	v_pk_mul_f32 v[2:3], v[10:11], v[2:3]
	v_pk_mul_f32 v[26:27], v[26:27], v[8:9]
	v_pk_mul_f32 v[22:23], v[22:23], v[2:3]
	v_pk_mul_f32 v[20:21], v[20:21], v[0:1]
	s_branch .LBB0_343

.LBB0_348:
	v_lshl_add_u32 v0, s36, 8, v169
	v_ashrrev_i32_e32 v1, 31, v0
	v_lshlrev_b64 v[2:3], 12, v[0:1]
	v_ashrrev_i32_e32 v165, 31, v164
	v_lshl_add_u64 v[2:3], s[8:9], 0, v[2:3]
	v_lshl_add_u64 v[2:3], v[2:3], 0, v[164:165]
	v_mov_b32_e32 v253, v252
	global_load_dwordx2 v[10:11], v253, s[100:101]
	global_load_dwordx2 v[12:13], v253, s[100:101] offset:512
	v_or_b32_e32 v18, 16, v0
	v_or_b32_e32 v166, 32, v0
	v_or_b32_e32 v4, 48, v0
	v_ashrrev_i32_e32 v19, 31, v18
	v_ashrrev_i32_e32 v167, 31, v166
	v_ashrrev_i32_e32 v5, 31, v4
	v_lshlrev_b64 v[2:3], 12, v[18:19]
	v_lshlrev_b64 v[6:7], 12, v[166:167]
	v_lshlrev_b64 v[8:9], 12, v[4:5]
	v_lshl_add_u64 v[2:3], s[8:9], 0, v[2:3]
	v_lshl_add_u64 v[6:7], s[8:9], 0, v[6:7]
	v_lshl_add_u64 v[8:9], s[8:9], 0, v[8:9]
	v_lshl_add_u64 v[2:3], v[2:3], 0, v[164:165]
	v_lshl_add_u64 v[6:7], v[6:7], 0, v[164:165]
	v_lshl_add_u64 v[172:173], v[8:9], 0, v[164:165]
	v_add_u32_e32 v253, 0x2000, v252
	global_load_dwordx2 v[174:175], v253, s[100:101]
	global_load_dwordx2 v[176:177], v253, s[100:101] offset:512
	v_add_u32_e32 v253, 0x4000, v252
	global_load_dwordx2 v[184:185], v253, s[100:101]
	global_load_dwordx2 v[8:9], v253, s[100:101] offset:512
	s_nop 0
	v_add_u32_e32 v253, 0x6000, v252
	global_load_dwordx2 v[6:7], v253, s[100:101]
	global_load_dwordx2 v[2:3], v253, s[100:101] offset:512
	v_lshlrev_b64 v[170:171], 11, v[0:1]
	v_mov_b32_e32 v14, 0
	v_mov_b32_e32 v15, 0
	s_mul_i32 s21, s40, 0x2400000
	s_mul_hi_i32 s19, s40, 0x2400000
	s_add_u32 s36, s22, s21
	s_addc_u32 s37, s23, s19
	v_lshlrev_b64 v[4:5], 11, v[4:5]
	v_lshl_add_u64 v[4:5], s[36:37], 0, v[4:5]
	v_lshl_add_u64 v[4:5], v[4:5], 0, v[164:165]
	s_and_b64 vcc, exec, s[6:7]
	s_mov_b64 s[6:7], -1
	s_waitcnt vmcnt(0)
	v_cvt_f32_ubyte0_e32 v1, v10
	v_cvt_f32_ubyte0_e32 v17, v11
	v_cvt_f32_ubyte1_e32 v172, v10
	v_cvt_f32_ubyte1_e32 v173, v11
	v_max_f32_e32 v1, 1.0, v1
	v_max_f32_e32 v17, 1.0, v17
	v_max_f32_e32 v172, 1.0, v172
	v_max_f32_e32 v173, 1.0, v173
	v_mul_f32_e32 v1, 0x39008081, v1
	v_mul_f32_e32 v17, 0x39008081, v17
	v_mul_f32_e32 v172, 0x39008081, v172
	v_mul_f32_e32 v173, 0x39008081, v173
	v_mul_f32_e32 v1, v144, v1
	v_mul_f32_e32 v144, v145, v172
	v_mul_f32_e32 v17, v140, v17
	v_mul_f32_e32 v140, v141, v173
	v_cvt_f32_ubyte2_e32 v183, v10
	v_cvt_f32_ubyte2_e32 v186, v11
	v_cvt_f32_ubyte3_e32 v10, v10
	v_cvt_f32_ubyte3_e32 v11, v11
	v_cvt_pk_fp8_f32 v14, v1, v144
	v_cvt_pk_fp8_f32 v15, v17, v140
	v_cvt_f32_ubyte0_e32 v187, v12
	v_cvt_f32_ubyte1_e32 v189, v12
	v_max_f32_e32 v183, 1.0, v183
	v_max_f32_e32 v186, 1.0, v186
	v_max_f32_e32 v10, 1.0, v10
	v_max_f32_e32 v11, 1.0, v11
	v_cvt_f32_ubyte0_e32 v188, v13
	v_cvt_f32_ubyte1_e32 v190, v13
	v_max_f32_e32 v187, 1.0, v187
	v_max_f32_e32 v189, 1.0, v189
	v_mul_f32_e32 v183, 0x39008081, v183
	v_mul_f32_e32 v186, 0x39008081, v186
	v_mul_f32_e32 v10, 0x39008081, v10
	v_mul_f32_e32 v11, 0x39008081, v11
	v_cvt_f32_ubyte2_e32 v192, v13
	v_cvt_f32_ubyte3_e32 v13, v13
	v_max_f32_e32 v188, 1.0, v188
	v_max_f32_e32 v190, 1.0, v190
	v_mul_f32_e32 v187, 0x39008081, v187
	v_mul_f32_e32 v189, 0x39008081, v189
	v_mul_f32_e32 v145, v146, v183
	v_mul_f32_e32 v10, v147, v10
	v_mul_f32_e32 v1, v142, v186
	v_mul_f32_e32 v11, v143, v11
	v_mul_f32_e32 v188, 0x39008081, v188
	v_mul_f32_e32 v190, 0x39008081, v190
	v_cvt_pk_fp8_f32 v14, v145, v10 op_sel:[0,0,1]
	v_cvt_pk_fp8_f32 v15, v1, v11 op_sel:[0,0,1]
	v_max_f32_e32 v1, 1.0, v13
	v_mul_f32_e32 v11, v136, v187
	v_mul_f32_e32 v13, v137, v189
	v_mov_b32_e32 v10, 0
	v_cvt_f32_ubyte2_e32 v191, v12
	v_cvt_f32_ubyte3_e32 v12, v12
	v_cvt_pk_fp8_f32 v10, v11, v13
	v_mul_f32_e32 v17, v132, v188
	v_mul_f32_e32 v132, v133, v190
	v_mov_b32_e32 v11, 0
	v_max_f32_e32 v191, 1.0, v191
	v_max_f32_e32 v12, 1.0, v12
	v_cvt_pk_fp8_f32 v11, v17, v132
	v_max_f32_e32 v192, 1.0, v192
	v_mul_f32_e32 v191, 0x39008081, v191
	v_mul_f32_e32 v12, 0x39008081, v12
	v_mul_f32_e32 v192, 0x39008081, v192
	v_mul_f32_e32 v1, 0x39008081, v1
	v_mul_f32_e32 v13, v138, v191
	v_mul_f32_e32 v12, v139, v12
	v_cvt_pk_fp8_f32 v10, v13, v12 op_sel:[0,0,1]
	v_mul_f32_e32 v12, v134, v192
	v_mul_f32_e32 v1, v135, v1
	v_cvt_pk_fp8_f32 v11, v12, v1 op_sel:[0,0,1]
	v_lshl_add_u64 v[12:13], s[36:37], 0, v[170:171]
	v_lshl_add_u64 v[12:13], v[12:13], 0, v[164:165]
	global_store_dwordx2 v[12:13], v[14:15], off
	global_store_dwordx2 v[12:13], v[10:11], off offset:128
	v_cvt_f32_ubyte0_e32 v12, v175
	v_max_f32_e32 v12, 1.0, v12
	v_cvt_f32_ubyte0_e32 v1, v174
	v_mul_f32_e32 v13, 0x39008081, v12
	v_cvt_f32_ubyte1_e32 v12, v174
	v_lshlrev_b64 v[10:11], 11, v[18:19]
	v_max_f32_e32 v1, 1.0, v1
	v_max_f32_e32 v12, 1.0, v12
	v_cvt_f32_ubyte1_e32 v14, v175
	v_cvt_f32_ubyte2_e32 v15, v174
	v_cvt_f32_ubyte3_e32 v18, v174
	v_mul_f32_e32 v1, 0x39008081, v1
	v_mul_f32_e32 v12, 0x39008081, v12
	v_max_f32_e32 v14, 1.0, v14
	v_max_f32_e32 v15, 1.0, v15
	v_max_f32_e32 v18, 1.0, v18
	v_mul_f32_e32 v14, 0x39008081, v14
	v_mul_f32_e32 v15, 0x39008081, v15
	v_mul_f32_e32 v18, 0x39008081, v18
	v_mul_f32_e32 v1, v128, v1
	v_mul_f32_e32 v128, v129, v12
	v_mov_b32_e32 v12, 0
	v_cvt_pk_fp8_f32 v12, v1, v128
	v_mul_f32_e32 v1, v130, v15
	v_mul_f32_e32 v15, v131, v18
	v_mul_f32_e32 v18, v124, v13
	v_mul_f32_e32 v14, v125, v14
	v_mov_b32_e32 v13, 0
	v_cvt_f32_ubyte2_e32 v17, v175
	v_cvt_f32_ubyte3_e32 v19, v175
	v_cvt_pk_fp8_f32 v13, v18, v14
	v_max_f32_e32 v17, 1.0, v17
	v_max_f32_e32 v19, 1.0, v19
	v_mul_f32_e32 v17, 0x39008081, v17
	v_mul_f32_e32 v19, 0x39008081, v19
	v_cvt_pk_fp8_f32 v12, v1, v15 op_sel:[0,0,1]
	v_mul_f32_e32 v1, v126, v17
	v_mul_f32_e32 v14, v127, v19
	v_cvt_pk_fp8_f32 v13, v1, v14 op_sel:[0,0,1]
	v_cvt_f32_ubyte0_e32 v14, v177
	v_max_f32_e32 v14, 1.0, v14
	v_cvt_f32_ubyte0_e32 v1, v176
	v_mul_f32_e32 v15, 0x39008081, v14
	v_cvt_f32_ubyte1_e32 v14, v176
	v_max_f32_e32 v1, 1.0, v1
	v_max_f32_e32 v14, 1.0, v14
	v_cvt_f32_ubyte1_e32 v17, v177
	v_mul_f32_e32 v1, 0x39008081, v1
	v_mul_f32_e32 v14, 0x39008081, v14
	v_max_f32_e32 v17, 1.0, v17
	v_mul_f32_e32 v17, 0x39008081, v17
	v_mul_f32_e32 v1, v120, v1
	v_mul_f32_e32 v120, v121, v14
	v_mov_b32_e32 v14, 0
	v_cvt_f32_ubyte2_e32 v18, v176
	v_cvt_f32_ubyte3_e32 v124, v176
	v_cvt_pk_fp8_f32 v14, v1, v120
	v_mul_f32_e32 v116, v116, v15
	v_mul_f32_e32 v17, v117, v17
	v_mov_b32_e32 v15, 0
	v_max_f32_e32 v18, 1.0, v18
	v_cvt_f32_ubyte2_e32 v19, v177
	v_max_f32_e32 v124, 1.0, v124
	v_cvt_f32_ubyte3_e32 v125, v177
	v_cvt_pk_fp8_f32 v15, v116, v17
	v_mul_f32_e32 v18, 0x39008081, v18
	v_max_f32_e32 v19, 1.0, v19
	v_mul_f32_e32 v124, 0x39008081, v124
	v_max_f32_e32 v125, 1.0, v125
	v_mul_f32_e32 v19, 0x39008081, v19
	v_mul_f32_e32 v125, 0x39008081, v125
	v_mul_f32_e32 v1, v122, v18
	v_mul_f32_e32 v18, v123, v124
	v_cvt_pk_fp8_f32 v14, v1, v18 op_sel:[0,0,1]
	v_mul_f32_e32 v1, v118, v19
	v_mul_f32_e32 v17, v119, v125
	v_cvt_pk_fp8_f32 v15, v1, v17 op_sel:[0,0,1]
	v_lshl_add_u64 v[10:11], s[36:37], 0, v[10:11]
	v_lshl_add_u64 v[10:11], v[10:11], 0, v[164:165]
	global_store_dwordx2 v[10:11], v[12:13], off
	global_store_dwordx2 v[10:11], v[14:15], off offset:128
	v_cvt_f32_ubyte0_e32 v12, v185
	v_max_f32_e32 v12, 1.0, v12
	v_cvt_f32_ubyte0_e32 v1, v184
	v_mul_f32_e32 v13, 0x39008081, v12
	v_cvt_f32_ubyte1_e32 v12, v184
	v_max_f32_e32 v1, 1.0, v1
	v_max_f32_e32 v12, 1.0, v12
	v_cvt_f32_ubyte1_e32 v14, v185
	v_cvt_f32_ubyte2_e32 v15, v184
	v_cvt_f32_ubyte3_e32 v18, v184
	v_mul_f32_e32 v1, 0x39008081, v1
	v_mul_f32_e32 v12, 0x39008081, v12
	v_max_f32_e32 v14, 1.0, v14
	v_max_f32_e32 v15, 1.0, v15
	v_max_f32_e32 v18, 1.0, v18
	v_mul_f32_e32 v14, 0x39008081, v14
	v_mul_f32_e32 v15, 0x39008081, v15
	v_mul_f32_e32 v18, 0x39008081, v18
	v_mul_f32_e32 v1, v112, v1
	v_mul_f32_e32 v112, v113, v12
	v_mov_b32_e32 v12, 0
	v_cvt_pk_fp8_f32 v12, v1, v112
	v_mul_f32_e32 v1, v114, v15
	v_mul_f32_e32 v15, v115, v18
	v_mul_f32_e32 v18, v108, v13
	v_mul_f32_e32 v14, v109, v14
	v_mov_b32_e32 v13, 0
	v_cvt_f32_ubyte2_e32 v17, v185
	v_cvt_f32_ubyte3_e32 v19, v185
	v_cvt_pk_fp8_f32 v13, v18, v14
	v_max_f32_e32 v17, 1.0, v17
	v_max_f32_e32 v19, 1.0, v19
	v_mul_f32_e32 v17, 0x39008081, v17
	v_mul_f32_e32 v19, 0x39008081, v19
	v_cvt_pk_fp8_f32 v12, v1, v15 op_sel:[0,0,1]
	v_mul_f32_e32 v1, v110, v17
	v_mul_f32_e32 v14, v111, v19
	v_cvt_pk_fp8_f32 v13, v1, v14 op_sel:[0,0,1]
	v_cvt_f32_ubyte0_e32 v1, v8
	v_cvt_f32_ubyte1_e32 v15, v8
	v_cvt_f32_ubyte2_e32 v18, v8
	v_cvt_f32_ubyte3_e32 v8, v8
	v_max_f32_e32 v8, 1.0, v8
	v_max_f32_e32 v1, 1.0, v1
	v_cvt_f32_ubyte0_e32 v14, v9
	v_max_f32_e32 v15, 1.0, v15
	v_cvt_f32_ubyte1_e32 v17, v9
	v_mul_f32_e32 v108, 0x39008081, v8
	v_cvt_f32_ubyte3_e32 v8, v9
	v_mul_f32_e32 v1, 0x39008081, v1
	v_max_f32_e32 v14, 1.0, v14
	v_mul_f32_e32 v15, 0x39008081, v15
	v_max_f32_e32 v17, 1.0, v17
	v_max_f32_e32 v8, 1.0, v8
	v_mul_f32_e32 v14, 0x39008081, v14
	v_mul_f32_e32 v17, 0x39008081, v17
	v_cvt_f32_ubyte2_e32 v19, v9
	v_mul_f32_e32 v109, 0x39008081, v8
	v_mul_f32_e32 v1, v104, v1
	v_mul_f32_e32 v9, v105, v15
	v_mov_b32_e32 v8, 0
	v_cvt_pk_fp8_f32 v8, v1, v9
	v_mul_f32_e32 v14, v100, v14
	v_mul_f32_e32 v17, v101, v17
	v_mov_b32_e32 v9, 0
	v_max_f32_e32 v18, 1.0, v18
	v_cvt_pk_fp8_f32 v9, v14, v17
	v_mul_f32_e32 v18, 0x39008081, v18
	v_max_f32_e32 v19, 1.0, v19
	v_mul_f32_e32 v19, 0x39008081, v19
	v_mul_f32_e32 v1, v106, v18
	v_mul_f32_e32 v15, v107, v108
	v_cvt_pk_fp8_f32 v8, v1, v15 op_sel:[0,0,1]
	v_mul_f32_e32 v1, v102, v19
	v_mul_f32_e32 v14, v103, v109
	v_lshlrev_b64 v[10:11], 11, v[166:167]
	v_cvt_pk_fp8_f32 v9, v1, v14 op_sel:[0,0,1]
	v_lshl_add_u64 v[10:11], s[36:37], 0, v[10:11]
	v_lshl_add_u64 v[10:11], v[10:11], 0, v[164:165]
	global_store_dwordx2 v[10:11], v[12:13], off
	global_store_dwordx2 v[10:11], v[8:9], off offset:128
	v_cvt_f32_ubyte0_e32 v1, v6
	v_cvt_f32_ubyte1_e32 v9, v6
	v_cvt_f32_ubyte2_e32 v11, v6
	v_cvt_f32_ubyte3_e32 v6, v6
	v_max_f32_e32 v6, 1.0, v6
	v_max_f32_e32 v1, 1.0, v1
	v_cvt_f32_ubyte0_e32 v8, v7
	v_max_f32_e32 v9, 1.0, v9
	v_cvt_f32_ubyte1_e32 v10, v7
	v_mul_f32_e32 v13, 0x39008081, v6
	v_cvt_f32_ubyte3_e32 v6, v7
	v_mul_f32_e32 v1, 0x39008081, v1
	v_max_f32_e32 v8, 1.0, v8
	v_mul_f32_e32 v9, 0x39008081, v9
	v_max_f32_e32 v10, 1.0, v10
	v_max_f32_e32 v6, 1.0, v6
	v_mul_f32_e32 v8, 0x39008081, v8
	v_mul_f32_e32 v10, 0x39008081, v10
	v_cvt_f32_ubyte2_e32 v12, v7
	v_mul_f32_e32 v14, 0x39008081, v6
	v_mul_f32_e32 v1, v96, v1
	v_mul_f32_e32 v7, v97, v9
	v_mov_b32_e32 v6, 0
	v_cvt_pk_fp8_f32 v6, v1, v7
	v_mul_f32_e32 v8, v92, v8
	v_mul_f32_e32 v10, v93, v10
	v_mov_b32_e32 v7, 0
	v_max_f32_e32 v11, 1.0, v11
	v_cvt_pk_fp8_f32 v7, v8, v10
	v_mul_f32_e32 v11, 0x39008081, v11
	v_max_f32_e32 v12, 1.0, v12
	v_mul_f32_e32 v12, 0x39008081, v12
	v_mul_f32_e32 v1, v98, v11
	v_mul_f32_e32 v9, v99, v13
	v_cvt_pk_fp8_f32 v6, v1, v9 op_sel:[0,0,1]
	v_mul_f32_e32 v1, v94, v12
	v_mul_f32_e32 v8, v95, v14
	v_cvt_pk_fp8_f32 v7, v1, v8 op_sel:[0,0,1]
	v_cvt_f32_ubyte0_e32 v1, v2
	v_cvt_f32_ubyte1_e32 v9, v2
	v_cvt_f32_ubyte2_e32 v11, v2
	v_cvt_f32_ubyte3_e32 v2, v2
	v_max_f32_e32 v2, 1.0, v2
	v_max_f32_e32 v1, 1.0, v1
	v_cvt_f32_ubyte0_e32 v8, v3
	v_max_f32_e32 v9, 1.0, v9
	v_cvt_f32_ubyte1_e32 v10, v3
	v_mul_f32_e32 v13, 0x39008081, v2
	v_cvt_f32_ubyte3_e32 v2, v3
	v_mul_f32_e32 v1, 0x39008081, v1
	v_max_f32_e32 v8, 1.0, v8
	v_mul_f32_e32 v9, 0x39008081, v9
	v_max_f32_e32 v10, 1.0, v10
	v_max_f32_e32 v2, 1.0, v2
	v_mul_f32_e32 v8, 0x39008081, v8
	v_mul_f32_e32 v10, 0x39008081, v10
	v_cvt_f32_ubyte2_e32 v12, v3
	v_mul_f32_e32 v14, 0x39008081, v2
	v_mul_f32_e32 v1, v88, v1
	v_mul_f32_e32 v3, v89, v9
	v_mov_b32_e32 v2, 0
	v_cvt_pk_fp8_f32 v2, v1, v3
	v_mul_f32_e32 v8, v84, v8
	v_mul_f32_e32 v10, v85, v10
	v_mov_b32_e32 v3, 0
	v_max_f32_e32 v11, 1.0, v11
	v_cvt_pk_fp8_f32 v3, v8, v10
	v_mul_f32_e32 v11, 0x39008081, v11
	v_max_f32_e32 v12, 1.0, v12
	v_mul_f32_e32 v12, 0x39008081, v12
	v_mul_f32_e32 v1, v90, v11
	v_mul_f32_e32 v9, v91, v13
	v_cvt_pk_fp8_f32 v2, v1, v9 op_sel:[0,0,1]
	v_mul_f32_e32 v1, v86, v12
	v_mul_f32_e32 v8, v87, v14
	v_cvt_pk_fp8_f32 v3, v1, v8 op_sel:[0,0,1]
	v_add_u32_e32 v8, 0x80, v0
	v_ashrrev_i32_e32 v9, 31, v8
	global_store_dwordx2 v[4:5], v[6:7], off
	global_store_dwordx2 v[4:5], v[2:3], off offset:128
	v_lshlrev_b64 v[2:3], 12, v[8:9]
	v_lshl_add_u64 v[2:3], s[8:9], 0, v[2:3]
	v_lshl_add_u64 v[2:3], v[2:3], 0, v[164:165]
	v_add_u32_e32 v253, 0x8000, v252
	global_load_dwordx2 v[10:11], v253, s[100:101]
	global_load_dwordx2 v[12:13], v253, s[100:101] offset:512
	v_add_u32_e32 v14, 0x90, v0
	v_ashrrev_i32_e32 v15, 31, v14
	v_lshlrev_b64 v[2:3], 12, v[14:15]
	v_lshl_add_u64 v[2:3], s[8:9], 0, v[2:3]
	v_lshl_add_u64 v[2:3], v[2:3], 0, v[164:165]
	v_add_u32_e32 v253, 0xa000, v252
	global_load_dwordx2 v[18:19], v253, s[100:101]
	global_load_dwordx2 v[84:85], v253, s[100:101] offset:512
	v_add_u32_e32 v86, 0xa0, v0
	v_add_u32_e32 v4, 0xb0, v0
	v_ashrrev_i32_e32 v87, 31, v86
	v_ashrrev_i32_e32 v5, 31, v4
	v_lshlrev_b64 v[2:3], 12, v[86:87]
	v_lshlrev_b64 v[0:1], 12, v[4:5]
	v_lshl_add_u64 v[2:3], s[8:9], 0, v[2:3]
	v_lshl_add_u64 v[0:1], s[8:9], 0, v[0:1]
	v_lshl_add_u64 v[2:3], v[2:3], 0, v[164:165]
	v_lshl_add_u64 v[0:1], v[0:1], 0, v[164:165]
	v_add_u32_e32 v253, 0xc000, v252
	global_load_dwordx2 v[88:89], v253, s[100:101]
	global_load_dwordx2 v[6:7], v253, s[100:101] offset:512
	s_nop 0
	v_add_u32_e32 v253, 0xe000, v252
	global_load_dwordx2 v[2:3], v253, s[100:101]
	s_nop 0
	global_load_dwordx2 v[0:1], v253, s[100:101] offset:512
	v_lshlrev_b64 v[8:9], 11, v[8:9]
	v_lshl_add_u64 v[8:9], s[36:37], 0, v[8:9]
	v_lshl_add_u64 v[8:9], v[8:9], 0, v[164:165]
	v_lshlrev_b64 v[4:5], 11, v[4:5]
	v_lshl_add_u64 v[4:5], s[36:37], 0, v[4:5]
	v_lshl_add_u64 v[4:5], v[4:5], 0, v[164:165]
	s_waitcnt vmcnt(7)
	v_cvt_f32_ubyte0_e32 v17, v10
	v_cvt_f32_ubyte1_e32 v91, v10
	v_cvt_f32_ubyte2_e32 v93, v10
	v_cvt_f32_ubyte3_e32 v10, v10
	v_max_f32_e32 v10, 1.0, v10
	v_max_f32_e32 v17, 1.0, v17
	v_cvt_f32_ubyte0_e32 v90, v11
	v_max_f32_e32 v91, 1.0, v91
	v_cvt_f32_ubyte1_e32 v92, v11
	v_mul_f32_e32 v95, 0x39008081, v10
	v_cvt_f32_ubyte3_e32 v10, v11
	v_mul_f32_e32 v17, 0x39008081, v17
	v_max_f32_e32 v90, 1.0, v90
	v_mul_f32_e32 v91, 0x39008081, v91
	v_max_f32_e32 v92, 1.0, v92
	v_max_f32_e32 v10, 1.0, v10
	v_mul_f32_e32 v90, 0x39008081, v90
	v_mul_f32_e32 v92, 0x39008081, v92
	v_cvt_f32_ubyte2_e32 v94, v11
	v_mul_f32_e32 v96, 0x39008081, v10
	v_mul_f32_e32 v11, v80, v17
	v_mul_f32_e32 v17, v81, v91
	v_mov_b32_e32 v10, 0
	v_cvt_pk_fp8_f32 v10, v11, v17
	v_mul_f32_e32 v76, v76, v90
	v_mul_f32_e32 v77, v77, v92
	v_mov_b32_e32 v11, 0
	v_max_f32_e32 v93, 1.0, v93
	v_cvt_pk_fp8_f32 v11, v76, v77
	v_mul_f32_e32 v93, 0x39008081, v93
	v_max_f32_e32 v94, 1.0, v94
	v_mul_f32_e32 v94, 0x39008081, v94
	v_mul_f32_e32 v17, v82, v93
	v_mul_f32_e32 v80, v83, v95
	v_cvt_pk_fp8_f32 v10, v17, v80 op_sel:[0,0,1]
	v_mul_f32_e32 v17, v78, v94
	v_mul_f32_e32 v76, v79, v96
	v_cvt_pk_fp8_f32 v11, v17, v76 op_sel:[0,0,1]
	s_waitcnt vmcnt(6)
	v_cvt_f32_ubyte0_e32 v17, v12
	v_cvt_f32_ubyte1_e32 v77, v12
	v_cvt_f32_ubyte2_e32 v79, v12
	v_cvt_f32_ubyte3_e32 v12, v12
	v_max_f32_e32 v12, 1.0, v12
	v_max_f32_e32 v17, 1.0, v17
	v_cvt_f32_ubyte0_e32 v76, v13
	v_max_f32_e32 v77, 1.0, v77
	v_cvt_f32_ubyte1_e32 v78, v13
	v_mul_f32_e32 v81, 0x39008081, v12
	v_cvt_f32_ubyte3_e32 v12, v13
	v_mul_f32_e32 v17, 0x39008081, v17
	v_max_f32_e32 v76, 1.0, v76
	v_mul_f32_e32 v77, 0x39008081, v77
	v_max_f32_e32 v78, 1.0, v78
	v_max_f32_e32 v12, 1.0, v12
	v_mul_f32_e32 v76, 0x39008081, v76
	v_mul_f32_e32 v78, 0x39008081, v78
	v_cvt_f32_ubyte2_e32 v80, v13
	v_mul_f32_e32 v82, 0x39008081, v12
	v_mul_f32_e32 v13, v72, v17
	v_mul_f32_e32 v17, v73, v77
	v_mov_b32_e32 v12, 0
	v_cvt_pk_fp8_f32 v12, v13, v17
	v_mul_f32_e32 v68, v68, v76
	v_mul_f32_e32 v69, v69, v78
	v_mov_b32_e32 v13, 0
	v_max_f32_e32 v79, 1.0, v79
	v_cvt_pk_fp8_f32 v13, v68, v69
	v_mul_f32_e32 v79, 0x39008081, v79
	v_max_f32_e32 v80, 1.0, v80
	v_mul_f32_e32 v80, 0x39008081, v80
	v_mul_f32_e32 v17, v74, v79
	v_mul_f32_e32 v72, v75, v81
	v_cvt_pk_fp8_f32 v12, v17, v72 op_sel:[0,0,1]
	v_mul_f32_e32 v17, v70, v80
	v_mul_f32_e32 v68, v71, v82
	v_cvt_pk_fp8_f32 v13, v17, v68 op_sel:[0,0,1]
	global_store_dwordx2 v[8:9], v[10:11], off
	global_store_dwordx2 v[8:9], v[12:13], off offset:128
	s_waitcnt vmcnt(7)
	v_cvt_f32_ubyte0_e32 v10, v18
	v_cvt_f32_ubyte1_e32 v12, v18
	v_lshlrev_b64 v[8:9], 11, v[14:15]
	v_max_f32_e32 v10, 1.0, v10
	v_cvt_f32_ubyte0_e32 v11, v19
	v_max_f32_e32 v12, 1.0, v12
	v_cvt_f32_ubyte1_e32 v13, v19
	v_cvt_f32_ubyte2_e32 v14, v18
	v_cvt_f32_ubyte3_e32 v17, v18
	v_mul_f32_e32 v10, 0x39008081, v10
	v_max_f32_e32 v11, 1.0, v11
	v_mul_f32_e32 v12, 0x39008081, v12
	v_max_f32_e32 v13, 1.0, v13
	v_max_f32_e32 v14, 1.0, v14
	v_max_f32_e32 v17, 1.0, v17
	v_mul_f32_e32 v11, 0x39008081, v11
	v_mul_f32_e32 v13, 0x39008081, v13
	v_mul_f32_e32 v14, 0x39008081, v14
	v_cvt_f32_ubyte2_e32 v15, v19
	v_mul_f32_e32 v17, 0x39008081, v17
	v_cvt_f32_ubyte3_e32 v18, v19
	v_mul_f32_e32 v19, v64, v10
	v_mul_f32_e32 v12, v65, v12
	v_mov_b32_e32 v10, 0
	v_cvt_pk_fp8_f32 v10, v19, v12
	v_mul_f32_e32 v12, v66, v14
	v_mul_f32_e32 v14, v67, v17
	v_mul_f32_e32 v17, v60, v11
	v_mul_f32_e32 v13, v61, v13
	v_mov_b32_e32 v11, 0
	v_cvt_pk_fp8_f32 v11, v17, v13
	v_max_f32_e32 v15, 1.0, v15
	v_max_f32_e32 v18, 1.0, v18
	v_mul_f32_e32 v15, 0x39008081, v15
	v_mul_f32_e32 v18, 0x39008081, v18
	v_cvt_pk_fp8_f32 v10, v12, v14 op_sel:[0,0,1]
	v_mul_f32_e32 v12, v62, v15
	v_mul_f32_e32 v13, v63, v18
	v_cvt_pk_fp8_f32 v11, v12, v13 op_sel:[0,0,1]
	s_waitcnt vmcnt(6)
	v_cvt_f32_ubyte0_e32 v12, v84
	v_cvt_f32_ubyte1_e32 v14, v84
	v_max_f32_e32 v12, 1.0, v12
	v_cvt_f32_ubyte0_e32 v13, v85
	v_max_f32_e32 v14, 1.0, v14
	v_cvt_f32_ubyte1_e32 v15, v85
	v_cvt_f32_ubyte2_e32 v17, v84
	v_cvt_f32_ubyte3_e32 v19, v84
	v_mul_f32_e32 v12, 0x39008081, v12
	v_max_f32_e32 v13, 1.0, v13
	v_mul_f32_e32 v14, 0x39008081, v14
	v_max_f32_e32 v15, 1.0, v15
	v_max_f32_e32 v17, 1.0, v17
	v_max_f32_e32 v19, 1.0, v19
	v_mul_f32_e32 v13, 0x39008081, v13
	v_mul_f32_e32 v15, 0x39008081, v15
	v_mul_f32_e32 v17, 0x39008081, v17
	v_mul_f32_e32 v19, 0x39008081, v19
	v_mul_f32_e32 v56, v56, v12
	v_mul_f32_e32 v14, v57, v14
	v_mov_b32_e32 v12, 0
	v_cvt_pk_fp8_f32 v12, v56, v14
	v_mul_f32_e32 v14, v58, v17
	v_mul_f32_e32 v17, v59, v19
	v_mul_f32_e32 v19, v52, v13
	v_mul_f32_e32 v15, v53, v15
	v_mov_b32_e32 v13, 0
	v_cvt_f32_ubyte2_e32 v18, v85
	v_cvt_f32_ubyte3_e32 v60, v85
	v_cvt_pk_fp8_f32 v13, v19, v15
	v_max_f32_e32 v18, 1.0, v18
	v_max_f32_e32 v60, 1.0, v60
	v_mul_f32_e32 v18, 0x39008081, v18
	v_mul_f32_e32 v60, 0x39008081, v60
	v_cvt_pk_fp8_f32 v12, v14, v17 op_sel:[0,0,1]
	v_mul_f32_e32 v14, v54, v18
	v_mul_f32_e32 v15, v55, v60
	v_cvt_pk_fp8_f32 v13, v14, v15 op_sel:[0,0,1]
	v_lshl_add_u64 v[8:9], s[36:37], 0, v[8:9]
	v_lshl_add_u64 v[8:9], v[8:9], 0, v[164:165]
	global_store_dwordx2 v[8:9], v[10:11], off
	global_store_dwordx2 v[8:9], v[12:13], off offset:128
	s_waitcnt vmcnt(7)
	v_cvt_f32_ubyte0_e32 v10, v88
	v_cvt_f32_ubyte1_e32 v12, v88
	v_max_f32_e32 v10, 1.0, v10
	v_cvt_f32_ubyte0_e32 v11, v89
	v_max_f32_e32 v12, 1.0, v12
	v_cvt_f32_ubyte1_e32 v13, v89
	v_cvt_f32_ubyte2_e32 v14, v88
	v_cvt_f32_ubyte3_e32 v17, v88
	v_mul_f32_e32 v10, 0x39008081, v10
	v_max_f32_e32 v11, 1.0, v11
	v_mul_f32_e32 v12, 0x39008081, v12
	v_max_f32_e32 v13, 1.0, v13
	v_max_f32_e32 v14, 1.0, v14
	v_max_f32_e32 v17, 1.0, v17
	v_mul_f32_e32 v11, 0x39008081, v11
	v_mul_f32_e32 v13, 0x39008081, v13
	v_mul_f32_e32 v14, 0x39008081, v14
	v_mul_f32_e32 v17, 0x39008081, v17
	v_mul_f32_e32 v19, v48, v10
	v_mul_f32_e32 v12, v49, v12
	v_mov_b32_e32 v10, 0
	v_cvt_pk_fp8_f32 v10, v19, v12
	v_mul_f32_e32 v12, v50, v14
	v_mul_f32_e32 v14, v51, v17
	v_mul_f32_e32 v17, v44, v11
	v_mul_f32_e32 v13, v45, v13
	v_mov_b32_e32 v11, 0
	v_cvt_f32_ubyte2_e32 v15, v89
	v_cvt_f32_ubyte3_e32 v18, v89
	v_cvt_pk_fp8_f32 v11, v17, v13
	v_max_f32_e32 v15, 1.0, v15
	v_max_f32_e32 v18, 1.0, v18
	v_mul_f32_e32 v15, 0x39008081, v15
	v_mul_f32_e32 v18, 0x39008081, v18
	v_cvt_pk_fp8_f32 v10, v12, v14 op_sel:[0,0,1]
	v_mul_f32_e32 v12, v46, v15
	v_mul_f32_e32 v13, v47, v18
	v_cvt_pk_fp8_f32 v11, v12, v13 op_sel:[0,0,1]
	s_waitcnt vmcnt(6)
	v_cvt_f32_ubyte0_e32 v12, v6
	v_cvt_f32_ubyte1_e32 v14, v6
	v_cvt_f32_ubyte2_e32 v17, v6
	v_cvt_f32_ubyte3_e32 v6, v6
	v_max_f32_e32 v6, 1.0, v6
	v_max_f32_e32 v12, 1.0, v12
	v_cvt_f32_ubyte0_e32 v13, v7
	v_max_f32_e32 v14, 1.0, v14
	v_cvt_f32_ubyte1_e32 v15, v7
	v_mul_f32_e32 v19, 0x39008081, v6
	v_cvt_f32_ubyte3_e32 v6, v7
	v_mul_f32_e32 v12, 0x39008081, v12
	v_max_f32_e32 v13, 1.0, v13
	v_mul_f32_e32 v14, 0x39008081, v14
	v_max_f32_e32 v15, 1.0, v15
	v_max_f32_e32 v6, 1.0, v6
	v_mul_f32_e32 v13, 0x39008081, v13
	v_mul_f32_e32 v15, 0x39008081, v15
	v_cvt_f32_ubyte2_e32 v18, v7
	v_mul_f32_e32 v44, 0x39008081, v6
	v_mul_f32_e32 v7, v40, v12
	v_mul_f32_e32 v12, v41, v14
	v_mov_b32_e32 v6, 0
	v_cvt_pk_fp8_f32 v6, v7, v12
	v_mul_f32_e32 v13, v36, v13
	v_mul_f32_e32 v15, v37, v15
	v_mov_b32_e32 v7, 0
	v_max_f32_e32 v17, 1.0, v17
	v_cvt_pk_fp8_f32 v7, v13, v15
	v_mul_f32_e32 v17, 0x39008081, v17
	v_max_f32_e32 v18, 1.0, v18
	v_mul_f32_e32 v18, 0x39008081, v18
	v_mul_f32_e32 v12, v42, v17
	v_mul_f32_e32 v14, v43, v19
	v_cvt_pk_fp8_f32 v6, v12, v14 op_sel:[0,0,1]
	v_mul_f32_e32 v12, v38, v18
	v_mul_f32_e32 v13, v39, v44
	v_lshlrev_b64 v[8:9], 11, v[86:87]
	v_cvt_pk_fp8_f32 v7, v12, v13 op_sel:[0,0,1]
	v_lshl_add_u64 v[8:9], s[36:37], 0, v[8:9]
	v_lshl_add_u64 v[8:9], v[8:9], 0, v[164:165]
	global_store_dwordx2 v[8:9], v[10:11], off
	global_store_dwordx2 v[8:9], v[6:7], off offset:128
	s_waitcnt vmcnt(7)
	v_cvt_f32_ubyte0_e32 v6, v2
	v_cvt_f32_ubyte1_e32 v8, v2
	v_cvt_f32_ubyte2_e32 v10, v2
	v_cvt_f32_ubyte3_e32 v2, v2
	v_max_f32_e32 v2, 1.0, v2
	v_max_f32_e32 v6, 1.0, v6
	v_cvt_f32_ubyte0_e32 v7, v3
	v_max_f32_e32 v8, 1.0, v8
	v_cvt_f32_ubyte1_e32 v9, v3
	v_mul_f32_e32 v12, 0x39008081, v2
	v_cvt_f32_ubyte3_e32 v2, v3
	v_mul_f32_e32 v6, 0x39008081, v6
	v_max_f32_e32 v7, 1.0, v7
	v_mul_f32_e32 v8, 0x39008081, v8
	v_max_f32_e32 v9, 1.0, v9
	v_max_f32_e32 v2, 1.0, v2
	v_mul_f32_e32 v7, 0x39008081, v7
	v_mul_f32_e32 v9, 0x39008081, v9
	v_cvt_f32_ubyte2_e32 v11, v3
	v_mul_f32_e32 v13, 0x39008081, v2
	v_mul_f32_e32 v3, v32, v6
	v_mul_f32_e32 v6, v33, v8
	v_mov_b32_e32 v2, 0
	v_cvt_pk_fp8_f32 v2, v3, v6
	v_mul_f32_e32 v7, v28, v7
	v_mul_f32_e32 v9, v29, v9
	v_mov_b32_e32 v3, 0
	v_max_f32_e32 v10, 1.0, v10
	v_cvt_pk_fp8_f32 v3, v7, v9
	v_mul_f32_e32 v10, 0x39008081, v10
	v_max_f32_e32 v11, 1.0, v11
	v_mul_f32_e32 v11, 0x39008081, v11
	v_mul_f32_e32 v6, v34, v10
	v_mul_f32_e32 v8, v35, v12
	v_cvt_pk_fp8_f32 v2, v6, v8 op_sel:[0,0,1]
	v_mul_f32_e32 v6, v30, v11
	v_mul_f32_e32 v7, v31, v13
	v_cvt_pk_fp8_f32 v3, v6, v7 op_sel:[0,0,1]
	s_waitcnt vmcnt(6)
	v_cvt_f32_ubyte0_e32 v6, v0
	v_cvt_f32_ubyte1_e32 v8, v0
	v_cvt_f32_ubyte2_e32 v10, v0
	v_cvt_f32_ubyte3_e32 v0, v0
	v_max_f32_e32 v0, 1.0, v0
	v_max_f32_e32 v6, 1.0, v6
	v_cvt_f32_ubyte0_e32 v7, v1
	v_max_f32_e32 v8, 1.0, v8
	v_cvt_f32_ubyte1_e32 v9, v1
	v_mul_f32_e32 v12, 0x39008081, v0
	v_cvt_f32_ubyte3_e32 v0, v1
	v_mul_f32_e32 v6, 0x39008081, v6
	v_max_f32_e32 v7, 1.0, v7
	v_mul_f32_e32 v8, 0x39008081, v8
	v_max_f32_e32 v9, 1.0, v9
	v_max_f32_e32 v0, 1.0, v0
	v_mul_f32_e32 v7, 0x39008081, v7
	v_mul_f32_e32 v9, 0x39008081, v9
	v_cvt_f32_ubyte2_e32 v11, v1
	v_mul_f32_e32 v13, 0x39008081, v0
	v_mul_f32_e32 v1, v24, v6
	v_mul_f32_e32 v6, v25, v8
	v_mov_b32_e32 v0, 0
	v_cvt_pk_fp8_f32 v0, v1, v6
	v_mul_f32_e32 v7, v20, v7
	v_mul_f32_e32 v9, v21, v9
	v_mov_b32_e32 v1, 0
	v_max_f32_e32 v10, 1.0, v10
	v_cvt_pk_fp8_f32 v1, v7, v9
	v_mul_f32_e32 v10, 0x39008081, v10
	v_max_f32_e32 v11, 1.0, v11
	v_mul_f32_e32 v11, 0x39008081, v11
	v_mul_f32_e32 v6, v26, v10
	v_mul_f32_e32 v8, v27, v12
	v_cvt_pk_fp8_f32 v0, v6, v8 op_sel:[0,0,1]
	v_mul_f32_e32 v6, v22, v11
	v_mul_f32_e32 v7, v23, v13
	v_cvt_pk_fp8_f32 v1, v6, v7 op_sel:[0,0,1]
	global_store_dwordx2 v[4:5], v[2:3], off
	global_store_dwordx2 v[4:5], v[0:1], off offset:128
	s_cbranch_vccnz .LBB0_333
	s_andn2_b64 vcc, exec, s[12:13]
	s_cbranch_vccnz .LBB0_332
	s_barrier
	s_branch .LBB0_332

	.amdhsa_kernel _Z14fwd_megakernel4Args
		.amdhsa_group_segment_fixed_size 147456
		.amdhsa_private_segment_fixed_size 0
		.amdhsa_kernarg_size 400
		.amdhsa_user_sgpr_count 2
		.amdhsa_user_sgpr_dispatch_ptr 0
		.amdhsa_user_sgpr_queue_ptr 0
		.amdhsa_user_sgpr_kernarg_segment_ptr 1
		.amdhsa_user_sgpr_dispatch_id 0
		.amdhsa_user_sgpr_kernarg_preload_length 0
		.amdhsa_user_sgpr_kernarg_preload_offset 0
		.amdhsa_user_sgpr_private_segment_size 0
		.amdhsa_uses_dynamic_stack 0
		.amdhsa_enable_private_segment 0
		.amdhsa_system_sgpr_workgroup_id_x 1
		.amdhsa_system_sgpr_workgroup_id_y 0
		.amdhsa_system_sgpr_workgroup_id_z 0
		.amdhsa_system_sgpr_workgroup_info 0
		.amdhsa_system_vgpr_workitem_id 2
		.amdhsa_next_free_vgpr 256
		.amdhsa_next_free_sgpr 102
		.amdhsa_accum_offset 256
		.amdhsa_reserve_vcc 1
		.amdhsa_float_round_mode_32 0
		.amdhsa_float_round_mode_16_64 0
		.amdhsa_float_denorm_mode_32 3
		.amdhsa_float_denorm_mode_16_64 3
		.amdhsa_dx10_clamp 1
		.amdhsa_ieee_mode 1
		.amdhsa_fp16_overflow 0
		.amdhsa_tg_split 0
		.amdhsa_exception_fp_ieee_invalid_op 0
		.amdhsa_exception_fp_denorm_src 0
		.amdhsa_exception_fp_ieee_div_zero 0
		.amdhsa_exception_fp_ieee_overflow 0
		.amdhsa_exception_fp_ieee_underflow 0
		.amdhsa_exception_fp_ieee_inexact 0
		.amdhsa_exception_int_div_zero 0
	.end_amdhsa_kernel

amdhsa.kernels:
  - .agpr_count:     0
    .args:
      - .offset:         0
        .size:           144
        .value_kind:     by_value
      - .offset:         144
        .size:           4
        .value_kind:     hidden_block_count_x
      - .offset:         148
        .size:           4
        .value_kind:     hidden_block_count_y
      - .offset:         152
        .size:           4
        .value_kind:     hidden_block_count_z
      - .offset:         156
        .size:           2
        .value_kind:     hidden_group_size_x
      - .offset:         158
        .size:           2
        .value_kind:     hidden_group_size_y
      - .offset:         160
        .size:           2
        .value_kind:     hidden_group_size_z
      - .offset:         162
        .size:           2
        .value_kind:     hidden_remainder_x
      - .offset:         164
        .size:           2
        .value_kind:     hidden_remainder_y
      - .offset:         166
        .size:           2
        .value_kind:     hidden_remainder_z
      - .offset:         184
        .size:           8
        .value_kind:     hidden_global_offset_x
      - .offset:         192
        .size:           8
        .value_kind:     hidden_global_offset_y
      - .offset:         200
        .size:           8
        .value_kind:     hidden_global_offset_z
      - .offset:         208
        .size:           2
        .value_kind:     hidden_grid_dims
      - .offset:         232
        .size:           8
        .value_kind:     hidden_multigrid_sync_arg
    .group_segment_fixed_size: 147456
    .kernarg_segment_align: 8
    .kernarg_segment_size: 400
    .language:       OpenCL C
    .language_version:
      - 2
      - 0
    .max_flat_workgroup_size: 512
    .name:           _Z14fwd_megakernel4Args
    .private_segment_fixed_size: 0
    .sgpr_count:     108
    .sgpr_spill_count: 2
    .symbol:         _Z14fwd_megakernel4Args.kd
    .uniform_work_group_size: 1
    .uses_dynamic_stack: false
    .vgpr_count:     256
    .vgpr_spill_count: 0
    .wavefront_size: 64
